# scan consumer: fourth operand register set moved from v106 to v184 (all set bases multiples of 4), otherwise the aligned version
# speedup vs baseline: 1.0222x; 1.0041x over previous
.Lscan_cons_chunk:
	s_nop 0
	v_cndmask_b32_e64 v2, v4, v5, s[42:43]
	v_add_lshl_u32 v2, v2, s80, 10
	v_mov_b32_e64 v3, v180
	s_add_i32 s28, s28, 0x10000
	v_lshl_add_u64 v[2:3], v[0:1], 0, v[2:3]
	v_add_u32_e64 v5, 64, v5
	v_subrev_u32_e64 v4, 64, v4
	s_waitcnt lgkmcnt(0)
	s_nop 0
	ds_read_b128 v[88:91], v10 offset:2304
	ds_read_b128 v[96:99], v10 offset:2816
	ds_read_b128 v[92:95], v10 offset:2560
	v_fma_mix_f32 v12, v6, v20, v180 op_sel_hi:[0,1,0]
	v_fma_mix_f32 v12, v7, v20, v12 op_sel:[0,1,0] op_sel_hi:[0,1,0]
	v_fma_mix_f32 v12, v8, v21, v12 op_sel_hi:[0,1,0]
	v_fma_mix_f32 v12, v9, v21, v12 op_sel:[0,1,0] op_sel_hi:[0,1,0]
	s_nop 1
	s_nop 0
	v_add_f32_dpp v12, v12, v12 row_ror:1 row_mask:0xf bank_mask:0xf bound_ctrl:1
	s_nop 1
	s_nop 0
	v_add_f32_dpp v12, v12, v12 row_ror:2 row_mask:0xf bank_mask:0xf bound_ctrl:1
	v_pk_fma_f32 v[48:49], v[28:29], v[66:67], v[6:7] op_sel_hi:[1,0,1]
	v_pk_fma_f32 v[50:51], v[30:31], v[66:67], v[8:9] op_sel_hi:[1,0,1]
	v_add_f32_dpp v12, v12, v12 row_ror:4 row_mask:0xf bank_mask:0xf bound_ctrl:1
	v_add_f32_dpp v130, v130, v130 row_ror:8 row_mask:0xf bank_mask:0xc
	v_add_f32_dpp v130, v122, v122 row_ror:8 row_mask:0xf bank_mask:0x3
	v_add_f32_dpp v131, v131, v131 row_ror:8 row_mask:0xf bank_mask:0xc
	v_add_f32_dpp v12, v12, v12 row_ror:8 row_mask:0xf bank_mask:0xf bound_ctrl:1
	v_pk_fma_f32 v[6:7], v[24:25], v[12:13], v[48:49] op_sel_hi:[1,0,1] neg_lo:[1,0,0] neg_hi:[1,0,0]
	v_pk_fma_f32 v[8:9], v[26:27], v[12:13], v[50:51] op_sel_hi:[1,0,1] neg_lo:[1,0,0] neg_hi:[1,0,0]
	ds_read_b128 v[188:191], v10 offset:3328
	ds_read_b128 v[184:187], v10 offset:3072
	ds_read_b128 v[196:199], v10 offset:3840
	ds_read_b128 v[192:195], v10 offset:3584
	ds_read_b128 v[70:73], v11 offset:256
	v_fma_mix_f32 v12, v6, v36, v180 op_sel_hi:[0,1,0]
	v_fma_mix_f32 v12, v7, v36, v12 op_sel:[0,1,0] op_sel_hi:[0,1,0]
	v_fma_mix_f32 v12, v8, v37, v12 op_sel_hi:[0,1,0]
	v_fma_mix_f32 v12, v9, v37, v12 op_sel:[0,1,0] op_sel_hi:[0,1,0]
	v_fma_mix_f32 v52, v6, v22, v180 op_sel_hi:[0,1,0]
	v_fma_mix_f32 v52, v7, v22, v52 op_sel:[0,1,0] op_sel_hi:[0,1,0]
	v_add_f32_dpp v12, v12, v12 row_ror:1 row_mask:0xf bank_mask:0xf bound_ctrl:1
	v_fma_mix_f32 v52, v8, v23, v52 op_sel_hi:[0,1,0]
	v_fma_mix_f32 v52, v9, v23, v52 op_sel:[0,1,0] op_sel_hi:[0,1,0]
	v_add_f32_dpp v12, v12, v12 row_ror:2 row_mask:0xf bank_mask:0xf bound_ctrl:1
	v_pk_fma_f32 v[48:49], v[44:45], v[66:67], v[6:7] op_sel:[0,1,0]
	v_pk_fma_f32 v[50:51], v[46:47], v[66:67], v[8:9] op_sel:[0,1,0]
	v_add_f32_dpp v12, v12, v12 row_ror:4 row_mask:0xf bank_mask:0xf bound_ctrl:1
	v_add_f32_dpp v131, v123, v123 row_ror:8 row_mask:0xf bank_mask:0x3
	v_add_f32_dpp v132, v132, v132 row_ror:8 row_mask:0xf bank_mask:0xc
	v_add_f32_dpp v132, v124, v124 row_ror:8 row_mask:0xf bank_mask:0x3
	v_add_f32_dpp v12, v12, v12 row_ror:8 row_mask:0xf bank_mask:0xf bound_ctrl:1
	v_pk_fma_f32 v[6:7], v[40:41], v[12:13], v[48:49] op_sel_hi:[1,0,1] neg_lo:[1,0,0] neg_hi:[1,0,0]
	v_pk_fma_f32 v[8:9], v[42:43], v[12:13], v[50:51] op_sel_hi:[1,0,1] neg_lo:[1,0,0] neg_hi:[1,0,0]
	s_waitcnt lgkmcnt(1)
	s_nop 0
	ds_read_b128 v[20:23], v10 offset:4352
	ds_read_b128 v[28:31], v10 offset:4864
	ds_read_b128 v[24:27], v10 offset:4608
	v_fma_mix_f32 v12, v6, v88, v180 op_sel_hi:[0,1,0]
	v_fma_mix_f32 v12, v7, v88, v12 op_sel:[0,1,0] op_sel_hi:[0,1,0]
	v_fma_mix_f32 v12, v8, v89, v12 op_sel_hi:[0,1,0]
	v_fma_mix_f32 v12, v9, v89, v12 op_sel:[0,1,0] op_sel_hi:[0,1,0]
	v_fma_mix_f32 v53, v6, v38, v180 op_sel_hi:[0,1,0]
	v_fma_mix_f32 v53, v7, v38, v53 op_sel:[0,1,0] op_sel_hi:[0,1,0]
	v_add_f32_dpp v12, v12, v12 row_ror:1 row_mask:0xf bank_mask:0xf bound_ctrl:1
	v_fma_mix_f32 v53, v8, v39, v53 op_sel_hi:[0,1,0]
	v_fma_mix_f32 v53, v9, v39, v53 op_sel:[0,1,0] op_sel_hi:[0,1,0]
	v_add_f32_dpp v12, v12, v12 row_ror:2 row_mask:0xf bank_mask:0xf bound_ctrl:1
	v_pk_fma_f32 v[48:49], v[96:97], v[68:69], v[6:7] op_sel_hi:[1,0,1]
	v_pk_fma_f32 v[50:51], v[98:99], v[68:69], v[8:9] op_sel_hi:[1,0,1]
	v_add_f32_dpp v12, v12, v12 row_ror:4 row_mask:0xf bank_mask:0xf bound_ctrl:1
	v_add_f32_dpp v133, v133, v133 row_ror:8 row_mask:0xf bank_mask:0xc
	v_add_f32_dpp v133, v125, v125 row_ror:8 row_mask:0xf bank_mask:0x3
	v_add_f32_dpp v134, v134, v134 row_ror:8 row_mask:0xf bank_mask:0xc
	v_add_f32_dpp v12, v12, v12 row_ror:8 row_mask:0xf bank_mask:0xf bound_ctrl:1
	v_pk_fma_f32 v[6:7], v[92:93], v[12:13], v[48:49] op_sel_hi:[1,0,1] neg_lo:[1,0,0] neg_hi:[1,0,0]
	v_pk_fma_f32 v[8:9], v[94:95], v[12:13], v[50:51] op_sel_hi:[1,0,1] neg_lo:[1,0,0] neg_hi:[1,0,0]
	ds_read_b128 v[36:39], v10 offset:5376
	ds_read_b128 v[44:47], v10 offset:5888
	ds_read_b128 v[40:43], v10 offset:5632
	v_fma_mix_f32 v12, v6, v188, v180 op_sel_hi:[0,1,0]
	v_fma_mix_f32 v12, v7, v188, v12 op_sel:[0,1,0] op_sel_hi:[0,1,0]
	v_fma_mix_f32 v12, v8, v189, v12 op_sel_hi:[0,1,0]
	v_fma_mix_f32 v12, v9, v189, v12 op_sel:[0,1,0] op_sel_hi:[0,1,0]
	v_fma_mix_f32 v54, v6, v90, v180 op_sel_hi:[0,1,0]
	v_fma_mix_f32 v54, v7, v90, v54 op_sel:[0,1,0] op_sel_hi:[0,1,0]
	v_add_f32_dpp v12, v12, v12 row_ror:1 row_mask:0xf bank_mask:0xf bound_ctrl:1
	v_fma_mix_f32 v54, v8, v91, v54 op_sel_hi:[0,1,0]
	v_fma_mix_f32 v54, v9, v91, v54 op_sel:[0,1,0] op_sel_hi:[0,1,0]
	v_add_f32_dpp v12, v12, v12 row_ror:2 row_mask:0xf bank_mask:0xf bound_ctrl:1
	v_pk_fma_f32 v[48:49], v[196:197], v[68:69], v[6:7] op_sel:[0,1,0]
	v_pk_fma_f32 v[50:51], v[198:199], v[68:69], v[8:9] op_sel:[0,1,0]
	v_add_f32_dpp v12, v12, v12 row_ror:4 row_mask:0xf bank_mask:0xf bound_ctrl:1
	v_add_f32_dpp v134, v126, v126 row_ror:8 row_mask:0xf bank_mask:0x3
	v_add_f32_dpp v135, v135, v135 row_ror:8 row_mask:0xf bank_mask:0xc
	v_add_f32_dpp v135, v127, v127 row_ror:8 row_mask:0xf bank_mask:0x3
	v_add_f32_dpp v12, v12, v12 row_ror:8 row_mask:0xf bank_mask:0xf bound_ctrl:1
	v_pk_fma_f32 v[6:7], v[192:193], v[12:13], v[48:49] op_sel_hi:[1,0,1] neg_lo:[1,0,0] neg_hi:[1,0,0]
	v_pk_fma_f32 v[8:9], v[194:195], v[12:13], v[50:51] op_sel_hi:[1,0,1] neg_lo:[1,0,0] neg_hi:[1,0,0]
	v_pk_mul_f32 v[6:7], v[6:7], v[184:185]
	v_pk_mul_f32 v[8:9], v[8:9], v[186:187]
	s_waitcnt lgkmcnt(0)
	s_nop 0
	ds_read_b128 v[88:91], v10 offset:6400
	ds_read_b128 v[96:99], v10 offset:6912
	ds_read_b128 v[92:95], v10 offset:6656
	v_fma_mix_f32 v12, v6, v20, v180 op_sel_hi:[0,1,0]
	v_fma_mix_f32 v12, v7, v20, v12 op_sel:[0,1,0] op_sel_hi:[0,1,0]
	v_fma_mix_f32 v12, v8, v21, v12 op_sel_hi:[0,1,0]
	v_fma_mix_f32 v12, v9, v21, v12 op_sel:[0,1,0] op_sel_hi:[0,1,0]
	v_fma_mix_f32 v55, v6, v190, v180 op_sel_hi:[0,1,0]
	v_fma_mix_f32 v55, v7, v190, v55 op_sel:[0,1,0] op_sel_hi:[0,1,0]
	v_add_f32_dpp v12, v12, v12 row_ror:1 row_mask:0xf bank_mask:0xf bound_ctrl:1
	v_fma_mix_f32 v55, v8, v191, v55 op_sel_hi:[0,1,0]
	v_fma_mix_f32 v55, v9, v191, v55 op_sel:[0,1,0] op_sel_hi:[0,1,0]
	v_add_f32_dpp v12, v12, v12 row_ror:2 row_mask:0xf bank_mask:0xf bound_ctrl:1
	v_pk_fma_f32 v[48:49], v[28:29], v[70:71], v[6:7] op_sel_hi:[1,0,1]
	v_pk_fma_f32 v[50:51], v[30:31], v[70:71], v[8:9] op_sel_hi:[1,0,1]
	v_add_f32_dpp v12, v12, v12 row_ror:4 row_mask:0xf bank_mask:0xf bound_ctrl:1
	v_add_f32_dpp v136, v136, v136 row_ror:8 row_mask:0xf bank_mask:0xc
	v_add_f32_dpp v136, v128, v128 row_ror:8 row_mask:0xf bank_mask:0x3
	v_add_f32_dpp v12, v12, v12 row_ror:8 row_mask:0xf bank_mask:0xf bound_ctrl:1
	v_pk_fma_f32 v[6:7], v[24:25], v[12:13], v[48:49] op_sel_hi:[1,0,1] neg_lo:[1,0,0] neg_hi:[1,0,0]
	v_pk_fma_f32 v[8:9], v[26:27], v[12:13], v[50:51] op_sel_hi:[1,0,1] neg_lo:[1,0,0] neg_hi:[1,0,0]
	ds_read_b128 v[188:191], v10 offset:7424
	ds_read_b128 v[184:187], v10 offset:7168
	ds_read_b128 v[196:199], v10 offset:7936
	ds_read_b128 v[192:195], v10 offset:7680
	ds_read_b128 v[66:69], v11 offset:512
	v_fma_mix_f32 v12, v6, v36, v180 op_sel_hi:[0,1,0]
	v_fma_mix_f32 v12, v7, v36, v12 op_sel:[0,1,0] op_sel_hi:[0,1,0]
	v_fma_mix_f32 v12, v8, v37, v12 op_sel_hi:[0,1,0]
	v_fma_mix_f32 v12, v9, v37, v12 op_sel:[0,1,0] op_sel_hi:[0,1,0]
	v_fma_mix_f32 v56, v6, v22, v180 op_sel_hi:[0,1,0]
	v_fma_mix_f32 v56, v7, v22, v56 op_sel:[0,1,0] op_sel_hi:[0,1,0]
	v_add_f32_dpp v12, v12, v12 row_ror:1 row_mask:0xf bank_mask:0xf bound_ctrl:1
	v_fma_mix_f32 v56, v8, v23, v56 op_sel_hi:[0,1,0]
	v_fma_mix_f32 v56, v9, v23, v56 op_sel:[0,1,0] op_sel_hi:[0,1,0]
	v_add_f32_dpp v12, v12, v12 row_ror:2 row_mask:0xf bank_mask:0xf bound_ctrl:1
	v_pk_fma_f32 v[48:49], v[44:45], v[70:71], v[6:7] op_sel:[0,1,0]
	v_pk_fma_f32 v[50:51], v[46:47], v[70:71], v[8:9] op_sel:[0,1,0]
	v_add_f32_dpp v12, v12, v12 row_ror:4 row_mask:0xf bank_mask:0xf bound_ctrl:1
	v_add_f32_dpp v137, v137, v137 row_ror:8 row_mask:0xf bank_mask:0xc
	v_add_f32_dpp v137, v129, v129 row_ror:8 row_mask:0xf bank_mask:0x3
	v_add_f32_dpp v12, v12, v12 row_ror:8 row_mask:0xf bank_mask:0xf bound_ctrl:1
	v_pk_fma_f32 v[6:7], v[40:41], v[12:13], v[48:49] op_sel_hi:[1,0,1] neg_lo:[1,0,0] neg_hi:[1,0,0]
	v_pk_fma_f32 v[8:9], v[42:43], v[12:13], v[50:51] op_sel_hi:[1,0,1] neg_lo:[1,0,0] neg_hi:[1,0,0]
	s_waitcnt lgkmcnt(1)
	s_nop 0
	ds_read_b128 v[20:23], v10 offset:8448
	ds_read_b128 v[28:31], v10 offset:8960
	ds_read_b128 v[24:27], v10 offset:8704
	v_fma_mix_f32 v12, v6, v88, v180 op_sel_hi:[0,1,0]
	v_fma_mix_f32 v12, v7, v88, v12 op_sel:[0,1,0] op_sel_hi:[0,1,0]
	v_fma_mix_f32 v12, v8, v89, v12 op_sel_hi:[0,1,0]
	v_fma_mix_f32 v12, v9, v89, v12 op_sel:[0,1,0] op_sel_hi:[0,1,0]
	v_fma_mix_f32 v57, v6, v38, v180 op_sel_hi:[0,1,0]
	v_fma_mix_f32 v57, v7, v38, v57 op_sel:[0,1,0] op_sel_hi:[0,1,0]
	v_add_f32_dpp v12, v12, v12 row_ror:1 row_mask:0xf bank_mask:0xf bound_ctrl:1
	v_fma_mix_f32 v57, v8, v39, v57 op_sel_hi:[0,1,0]
	v_fma_mix_f32 v57, v9, v39, v57 op_sel:[0,1,0] op_sel_hi:[0,1,0]
	v_add_f32_dpp v12, v12, v12 row_ror:2 row_mask:0xf bank_mask:0xf bound_ctrl:1
	v_pk_fma_f32 v[48:49], v[96:97], v[72:73], v[6:7] op_sel_hi:[1,0,1]
	v_pk_fma_f32 v[50:51], v[98:99], v[72:73], v[8:9] op_sel_hi:[1,0,1]
	v_add_f32_dpp v12, v12, v12 row_ror:4 row_mask:0xf bank_mask:0xf bound_ctrl:1
	v_add_f32_dpp v134, v134, v134 row_ror:4 row_mask:0xf bank_mask:0xa
	v_add_f32_dpp v134, v130, v130 row_ror:12 row_mask:0xf bank_mask:0x5
	v_add_f32_dpp v135, v135, v135 row_ror:4 row_mask:0xf bank_mask:0xa
	v_add_f32_dpp v12, v12, v12 row_ror:8 row_mask:0xf bank_mask:0xf bound_ctrl:1
	v_pk_fma_f32 v[6:7], v[92:93], v[12:13], v[48:49] op_sel_hi:[1,0,1] neg_lo:[1,0,0] neg_hi:[1,0,0]
	v_pk_fma_f32 v[8:9], v[94:95], v[12:13], v[50:51] op_sel_hi:[1,0,1] neg_lo:[1,0,0] neg_hi:[1,0,0]
	ds_read_b128 v[36:39], v10 offset:9472
	ds_read_b128 v[44:47], v10 offset:9984
	ds_read_b128 v[40:43], v10 offset:9728
	v_fma_mix_f32 v12, v6, v188, v180 op_sel_hi:[0,1,0]
	v_fma_mix_f32 v12, v7, v188, v12 op_sel:[0,1,0] op_sel_hi:[0,1,0]
	v_fma_mix_f32 v12, v8, v189, v12 op_sel_hi:[0,1,0]
	v_fma_mix_f32 v12, v9, v189, v12 op_sel:[0,1,0] op_sel_hi:[0,1,0]
	v_fma_mix_f32 v81, v6, v90, v180 op_sel_hi:[0,1,0]
	v_fma_mix_f32 v81, v7, v90, v81 op_sel:[0,1,0] op_sel_hi:[0,1,0]
	v_add_f32_dpp v12, v12, v12 row_ror:1 row_mask:0xf bank_mask:0xf bound_ctrl:1
	v_fma_mix_f32 v81, v8, v91, v81 op_sel_hi:[0,1,0]
	v_fma_mix_f32 v81, v9, v91, v81 op_sel:[0,1,0] op_sel_hi:[0,1,0]
	v_add_f32_dpp v12, v12, v12 row_ror:2 row_mask:0xf bank_mask:0xf bound_ctrl:1
	v_pk_fma_f32 v[48:49], v[196:197], v[72:73], v[6:7] op_sel:[0,1,0]
	v_pk_fma_f32 v[50:51], v[198:199], v[72:73], v[8:9] op_sel:[0,1,0]
	v_add_f32_dpp v12, v12, v12 row_ror:4 row_mask:0xf bank_mask:0xf bound_ctrl:1
	v_add_f32_dpp v135, v131, v131 row_ror:12 row_mask:0xf bank_mask:0x5
	v_add_f32_dpp v136, v136, v136 row_ror:4 row_mask:0xf bank_mask:0xa
	v_add_f32_dpp v136, v132, v132 row_ror:12 row_mask:0xf bank_mask:0x5
	v_add_f32_dpp v12, v12, v12 row_ror:8 row_mask:0xf bank_mask:0xf bound_ctrl:1
	v_pk_fma_f32 v[6:7], v[192:193], v[12:13], v[48:49] op_sel_hi:[1,0,1] neg_lo:[1,0,0] neg_hi:[1,0,0]
	v_pk_fma_f32 v[8:9], v[194:195], v[12:13], v[50:51] op_sel_hi:[1,0,1] neg_lo:[1,0,0] neg_hi:[1,0,0]
	v_pk_mul_f32 v[6:7], v[6:7], v[184:185]
	v_pk_mul_f32 v[8:9], v[8:9], v[186:187]
	s_waitcnt lgkmcnt(0)
	s_nop 0
	ds_read_b128 v[88:91], v10 offset:10496
	ds_read_b128 v[96:99], v10 offset:11008
	ds_read_b128 v[92:95], v10 offset:10752
	v_fma_mix_f32 v12, v6, v20, v180 op_sel_hi:[0,1,0]
	v_fma_mix_f32 v12, v7, v20, v12 op_sel:[0,1,0] op_sel_hi:[0,1,0]
	v_fma_mix_f32 v12, v8, v21, v12 op_sel_hi:[0,1,0]
	v_fma_mix_f32 v12, v9, v21, v12 op_sel:[0,1,0] op_sel_hi:[0,1,0]
	v_fma_mix_f32 v82, v6, v190, v180 op_sel_hi:[0,1,0]
	v_fma_mix_f32 v82, v7, v190, v82 op_sel:[0,1,0] op_sel_hi:[0,1,0]
	v_add_f32_dpp v12, v12, v12 row_ror:1 row_mask:0xf bank_mask:0xf bound_ctrl:1
	v_fma_mix_f32 v82, v8, v191, v82 op_sel_hi:[0,1,0]
	v_fma_mix_f32 v82, v9, v191, v82 op_sel:[0,1,0] op_sel_hi:[0,1,0]
	v_add_f32_dpp v12, v12, v12 row_ror:2 row_mask:0xf bank_mask:0xf bound_ctrl:1
	v_pk_fma_f32 v[48:49], v[28:29], v[66:67], v[6:7] op_sel_hi:[1,0,1]
	v_pk_fma_f32 v[50:51], v[30:31], v[66:67], v[8:9] op_sel_hi:[1,0,1]
	v_add_f32_dpp v12, v12, v12 row_ror:4 row_mask:0xf bank_mask:0xf bound_ctrl:1
	v_add_f32_dpp v137, v137, v137 row_ror:4 row_mask:0xf bank_mask:0xa
	v_add_f32_dpp v137, v133, v133 row_ror:12 row_mask:0xf bank_mask:0x5
	v_add_f32_dpp v12, v12, v12 row_ror:8 row_mask:0xf bank_mask:0xf bound_ctrl:1
	v_pk_fma_f32 v[6:7], v[24:25], v[12:13], v[48:49] op_sel_hi:[1,0,1] neg_lo:[1,0,0] neg_hi:[1,0,0]
	v_pk_fma_f32 v[8:9], v[26:27], v[12:13], v[50:51] op_sel_hi:[1,0,1] neg_lo:[1,0,0] neg_hi:[1,0,0]
	ds_read_b128 v[188:191], v10 offset:11520
	ds_read_b128 v[184:187], v10 offset:11264
	ds_read_b128 v[196:199], v10 offset:12032
	ds_read_b128 v[192:195], v10 offset:11776
	ds_read_b128 v[70:73], v11 offset:768
	v_fma_mix_f32 v12, v6, v36, v180 op_sel_hi:[0,1,0]
	v_fma_mix_f32 v12, v7, v36, v12 op_sel:[0,1,0] op_sel_hi:[0,1,0]
	v_fma_mix_f32 v12, v8, v37, v12 op_sel_hi:[0,1,0]
	v_fma_mix_f32 v12, v9, v37, v12 op_sel:[0,1,0] op_sel_hi:[0,1,0]
	v_fma_mix_f32 v83, v6, v22, v180 op_sel_hi:[0,1,0]
	v_fma_mix_f32 v83, v7, v22, v83 op_sel:[0,1,0] op_sel_hi:[0,1,0]
	v_add_f32_dpp v12, v12, v12 row_ror:1 row_mask:0xf bank_mask:0xf bound_ctrl:1
	v_fma_mix_f32 v83, v8, v23, v83 op_sel_hi:[0,1,0]
	v_fma_mix_f32 v83, v9, v23, v83 op_sel:[0,1,0] op_sel_hi:[0,1,0]
	v_add_f32_dpp v12, v12, v12 row_ror:2 row_mask:0xf bank_mask:0xf bound_ctrl:1
	v_pk_fma_f32 v[48:49], v[44:45], v[66:67], v[6:7] op_sel:[0,1,0]
	v_pk_fma_f32 v[50:51], v[46:47], v[66:67], v[8:9] op_sel:[0,1,0]
	v_add_f32_dpp v12, v12, v12 row_ror:4 row_mask:0xf bank_mask:0xf bound_ctrl:1
	v_cndmask_b32_e64 v62, v136, v134, s[38:39]
	v_cndmask_b32_e64 v63, v134, v136, s[38:39]
	v_add_f32_dpp v12, v12, v12 row_ror:8 row_mask:0xf bank_mask:0xf bound_ctrl:1
	v_pk_fma_f32 v[6:7], v[40:41], v[12:13], v[48:49] op_sel_hi:[1,0,1] neg_lo:[1,0,0] neg_hi:[1,0,0]
	v_pk_fma_f32 v[8:9], v[42:43], v[12:13], v[50:51] op_sel_hi:[1,0,1] neg_lo:[1,0,0] neg_hi:[1,0,0]
	s_waitcnt lgkmcnt(1)
	s_nop 0
	ds_read_b128 v[20:23], v10 offset:12544
	ds_read_b128 v[28:31], v10 offset:13056
	ds_read_b128 v[24:27], v10 offset:12800
	v_fma_mix_f32 v12, v6, v88, v180 op_sel_hi:[0,1,0]
	v_fma_mix_f32 v12, v7, v88, v12 op_sel:[0,1,0] op_sel_hi:[0,1,0]
	v_fma_mix_f32 v12, v8, v89, v12 op_sel_hi:[0,1,0]
	v_fma_mix_f32 v12, v9, v89, v12 op_sel:[0,1,0] op_sel_hi:[0,1,0]
	v_fma_mix_f32 v100, v6, v38, v180 op_sel_hi:[0,1,0]
	v_fma_mix_f32 v100, v7, v38, v100 op_sel:[0,1,0] op_sel_hi:[0,1,0]
	v_add_f32_dpp v12, v12, v12 row_ror:1 row_mask:0xf bank_mask:0xf bound_ctrl:1
	v_fma_mix_f32 v100, v8, v39, v100 op_sel_hi:[0,1,0]
	v_fma_mix_f32 v100, v9, v39, v100 op_sel:[0,1,0] op_sel_hi:[0,1,0]
	v_add_f32_dpp v12, v12, v12 row_ror:2 row_mask:0xf bank_mask:0xf bound_ctrl:1
	v_pk_fma_f32 v[48:49], v[96:97], v[68:69], v[6:7] op_sel_hi:[1,0,1]
	v_pk_fma_f32 v[50:51], v[98:99], v[68:69], v[8:9] op_sel_hi:[1,0,1]
	v_add_f32_dpp v12, v12, v12 row_ror:4 row_mask:0xf bank_mask:0xf bound_ctrl:1
	v_cndmask_b32_e64 v64, v137, v135, s[38:39]
	v_cndmask_b32_e64 v65, v135, v137, s[38:39]
	v_add_f32_dpp v12, v12, v12 row_ror:8 row_mask:0xf bank_mask:0xf bound_ctrl:1
	v_pk_fma_f32 v[6:7], v[92:93], v[12:13], v[48:49] op_sel_hi:[1,0,1] neg_lo:[1,0,0] neg_hi:[1,0,0]
	v_pk_fma_f32 v[8:9], v[94:95], v[12:13], v[50:51] op_sel_hi:[1,0,1] neg_lo:[1,0,0] neg_hi:[1,0,0]
	ds_read_b128 v[36:39], v10 offset:13568
	ds_read_b128 v[44:47], v10 offset:14080
	ds_read_b128 v[40:43], v10 offset:13824
	v_fma_mix_f32 v12, v6, v188, v180 op_sel_hi:[0,1,0]
	v_fma_mix_f32 v12, v7, v188, v12 op_sel:[0,1,0] op_sel_hi:[0,1,0]
	v_fma_mix_f32 v12, v8, v189, v12 op_sel_hi:[0,1,0]
	v_fma_mix_f32 v12, v9, v189, v12 op_sel:[0,1,0] op_sel_hi:[0,1,0]
	v_fma_mix_f32 v101, v6, v90, v180 op_sel_hi:[0,1,0]
	v_fma_mix_f32 v101, v7, v90, v101 op_sel:[0,1,0] op_sel_hi:[0,1,0]
	v_add_f32_dpp v12, v12, v12 row_ror:1 row_mask:0xf bank_mask:0xf bound_ctrl:1
	v_fma_mix_f32 v101, v8, v91, v101 op_sel_hi:[0,1,0]
	v_fma_mix_f32 v101, v9, v91, v101 op_sel:[0,1,0] op_sel_hi:[0,1,0]
	v_add_f32_dpp v12, v12, v12 row_ror:2 row_mask:0xf bank_mask:0xf bound_ctrl:1
	v_pk_fma_f32 v[48:49], v[196:197], v[68:69], v[6:7] op_sel:[0,1,0]
	v_pk_fma_f32 v[50:51], v[198:199], v[68:69], v[8:9] op_sel:[0,1,0]
	v_add_f32_dpp v12, v12, v12 row_ror:4 row_mask:0xf bank_mask:0xf bound_ctrl:1
	v_add_f32_dpp v62, v63, v62 quad_perm:[2,3,0,1] row_mask:0xf bank_mask:0xf bound_ctrl:1
	v_add_f32_dpp v63, v65, v64 quad_perm:[2,3,0,1] row_mask:0xf bank_mask:0xf bound_ctrl:1
	v_add_f32_dpp v12, v12, v12 row_ror:8 row_mask:0xf bank_mask:0xf bound_ctrl:1
	v_pk_fma_f32 v[6:7], v[192:193], v[12:13], v[48:49] op_sel_hi:[1,0,1] neg_lo:[1,0,0] neg_hi:[1,0,0]
	v_pk_fma_f32 v[8:9], v[194:195], v[12:13], v[50:51] op_sel_hi:[1,0,1] neg_lo:[1,0,0] neg_hi:[1,0,0]
	v_pk_mul_f32 v[6:7], v[6:7], v[184:185]
	v_pk_mul_f32 v[8:9], v[8:9], v[186:187]
	s_waitcnt lgkmcnt(0)
	s_nop 0
	ds_read_b128 v[88:91], v10 offset:14592
	ds_read_b128 v[96:99], v10 offset:15104
	ds_read_b128 v[92:95], v10 offset:14848
	v_fma_mix_f32 v12, v6, v20, v180 op_sel_hi:[0,1,0]
	v_fma_mix_f32 v12, v7, v20, v12 op_sel:[0,1,0] op_sel_hi:[0,1,0]
	v_fma_mix_f32 v12, v8, v21, v12 op_sel_hi:[0,1,0]
	v_fma_mix_f32 v12, v9, v21, v12 op_sel:[0,1,0] op_sel_hi:[0,1,0]
	v_fma_mix_f32 v102, v6, v190, v180 op_sel_hi:[0,1,0]
	v_fma_mix_f32 v102, v7, v190, v102 op_sel:[0,1,0] op_sel_hi:[0,1,0]
	v_add_f32_dpp v12, v12, v12 row_ror:1 row_mask:0xf bank_mask:0xf bound_ctrl:1
	v_fma_mix_f32 v102, v8, v191, v102 op_sel_hi:[0,1,0]
	v_fma_mix_f32 v102, v9, v191, v102 op_sel:[0,1,0] op_sel_hi:[0,1,0]
	v_add_f32_dpp v12, v12, v12 row_ror:2 row_mask:0xf bank_mask:0xf bound_ctrl:1
	v_pk_fma_f32 v[48:49], v[28:29], v[70:71], v[6:7] op_sel_hi:[1,0,1]
	v_pk_fma_f32 v[50:51], v[30:31], v[70:71], v[8:9] op_sel_hi:[1,0,1]
	v_add_f32_dpp v12, v12, v12 row_ror:4 row_mask:0xf bank_mask:0xf bound_ctrl:1
	v_cndmask_b32_e64 v65, v63, v62, s[40:41]
	v_cndmask_b32_e64 v62, v62, v63, s[40:41]
	v_add_f32_dpp v12, v12, v12 row_ror:8 row_mask:0xf bank_mask:0xf bound_ctrl:1
	v_pk_fma_f32 v[6:7], v[24:25], v[12:13], v[48:49] op_sel_hi:[1,0,1] neg_lo:[1,0,0] neg_hi:[1,0,0]
	v_pk_fma_f32 v[8:9], v[26:27], v[12:13], v[50:51] op_sel_hi:[1,0,1] neg_lo:[1,0,0] neg_hi:[1,0,0]
	ds_read_b128 v[188:191], v10 offset:15616
	ds_read_b128 v[184:187], v10 offset:15360
	ds_read_b128 v[196:199], v10 offset:16128
	ds_read_b128 v[192:195], v10 offset:15872
	ds_read_b128 v[66:69], v11 offset:1024
	v_fma_mix_f32 v12, v6, v36, v180 op_sel_hi:[0,1,0]
	v_fma_mix_f32 v12, v7, v36, v12 op_sel:[0,1,0] op_sel_hi:[0,1,0]
	v_fma_mix_f32 v12, v8, v37, v12 op_sel_hi:[0,1,0]
	v_fma_mix_f32 v12, v9, v37, v12 op_sel:[0,1,0] op_sel_hi:[0,1,0]
	v_fma_mix_f32 v103, v6, v22, v180 op_sel_hi:[0,1,0]
	v_fma_mix_f32 v103, v7, v22, v103 op_sel:[0,1,0] op_sel_hi:[0,1,0]
	v_add_f32_dpp v12, v12, v12 row_ror:1 row_mask:0xf bank_mask:0xf bound_ctrl:1
	v_fma_mix_f32 v103, v8, v23, v103 op_sel_hi:[0,1,0]
	v_fma_mix_f32 v103, v9, v23, v103 op_sel:[0,1,0] op_sel_hi:[0,1,0]
	v_add_f32_dpp v12, v12, v12 row_ror:2 row_mask:0xf bank_mask:0xf bound_ctrl:1
	v_pk_fma_f32 v[48:49], v[44:45], v[70:71], v[6:7] op_sel:[0,1,0]
	v_pk_fma_f32 v[50:51], v[46:47], v[70:71], v[8:9] op_sel:[0,1,0]
	v_add_f32_dpp v12, v12, v12 row_ror:4 row_mask:0xf bank_mask:0xf bound_ctrl:1
	v_add_f32_dpp v62, v62, v65 quad_perm:[1,0,3,2] row_mask:0xf bank_mask:0xf bound_ctrl:1
	v_cvt_pk_bf16_f32 v62, v62, v62
	v_add_f32_dpp v12, v12, v12 row_ror:8 row_mask:0xf bank_mask:0xf bound_ctrl:1
	v_pk_fma_f32 v[6:7], v[40:41], v[12:13], v[48:49] op_sel_hi:[1,0,1] neg_lo:[1,0,0] neg_hi:[1,0,0]
	v_pk_fma_f32 v[8:9], v[42:43], v[12:13], v[50:51] op_sel_hi:[1,0,1] neg_lo:[1,0,0] neg_hi:[1,0,0]
	s_waitcnt lgkmcnt(1)
	s_nop 0
	ds_read_b128 v[20:23], v10 offset:16640
	ds_read_b128 v[28:31], v10 offset:17152
	ds_read_b128 v[24:27], v10 offset:16896
	v_fma_mix_f32 v12, v6, v88, v180 op_sel_hi:[0,1,0]
	v_fma_mix_f32 v12, v7, v88, v12 op_sel:[0,1,0] op_sel_hi:[0,1,0]
	v_fma_mix_f32 v12, v8, v89, v12 op_sel_hi:[0,1,0]
	v_fma_mix_f32 v12, v9, v89, v12 op_sel:[0,1,0] op_sel_hi:[0,1,0]
	v_fma_mix_f32 v104, v6, v38, v180 op_sel_hi:[0,1,0]
	v_fma_mix_f32 v104, v7, v38, v104 op_sel:[0,1,0] op_sel_hi:[0,1,0]
	v_add_f32_dpp v12, v12, v12 row_ror:1 row_mask:0xf bank_mask:0xf bound_ctrl:1
	v_fma_mix_f32 v104, v8, v39, v104 op_sel_hi:[0,1,0]
	v_fma_mix_f32 v104, v9, v39, v104 op_sel:[0,1,0] op_sel_hi:[0,1,0]
	v_add_f32_dpp v12, v12, v12 row_ror:2 row_mask:0xf bank_mask:0xf bound_ctrl:1
	v_pk_fma_f32 v[48:49], v[96:97], v[72:73], v[6:7] op_sel_hi:[1,0,1]
	v_pk_fma_f32 v[50:51], v[98:99], v[72:73], v[8:9] op_sel_hi:[1,0,1]
	v_add_f32_dpp v12, v12, v12 row_ror:4 row_mask:0xf bank_mask:0xf bound_ctrl:1
	s_mov_b64 exec, s[100:101]
	s_nop 0
	global_store_short v[170:171], v62, off
	s_mov_b64 exec, -1
	s_nop 0
	v_add_f32_dpp v12, v12, v12 row_ror:8 row_mask:0xf bank_mask:0xf bound_ctrl:1
	v_pk_fma_f32 v[6:7], v[92:93], v[12:13], v[48:49] op_sel_hi:[1,0,1] neg_lo:[1,0,0] neg_hi:[1,0,0]
	v_pk_fma_f32 v[8:9], v[94:95], v[12:13], v[50:51] op_sel_hi:[1,0,1] neg_lo:[1,0,0] neg_hi:[1,0,0]
	ds_read_b128 v[36:39], v10 offset:17664
	ds_read_b128 v[44:47], v10 offset:18176
	ds_read_b128 v[40:43], v10 offset:17920
	v_fma_mix_f32 v12, v6, v188, v180 op_sel_hi:[0,1,0]
	v_fma_mix_f32 v12, v7, v188, v12 op_sel:[0,1,0] op_sel_hi:[0,1,0]
	v_fma_mix_f32 v12, v8, v189, v12 op_sel_hi:[0,1,0]
	v_fma_mix_f32 v12, v9, v189, v12 op_sel:[0,1,0] op_sel_hi:[0,1,0]
	v_fma_mix_f32 v105, v6, v90, v180 op_sel_hi:[0,1,0]
	v_fma_mix_f32 v105, v7, v90, v105 op_sel:[0,1,0] op_sel_hi:[0,1,0]
	v_add_f32_dpp v12, v12, v12 row_ror:1 row_mask:0xf bank_mask:0xf bound_ctrl:1
	v_fma_mix_f32 v105, v8, v91, v105 op_sel_hi:[0,1,0]
	v_fma_mix_f32 v105, v9, v91, v105 op_sel:[0,1,0] op_sel_hi:[0,1,0]
	v_add_f32_dpp v12, v12, v12 row_ror:2 row_mask:0xf bank_mask:0xf bound_ctrl:1
	v_pk_fma_f32 v[48:49], v[196:197], v[72:73], v[6:7] op_sel:[0,1,0]
	v_pk_fma_f32 v[50:51], v[198:199], v[72:73], v[8:9] op_sel:[0,1,0]
	v_add_f32_dpp v12, v12, v12 row_ror:4 row_mask:0xf bank_mask:0xf bound_ctrl:1
	s_nop 1
	s_nop 0
	v_add_f32_dpp v12, v12, v12 row_ror:8 row_mask:0xf bank_mask:0xf bound_ctrl:1
	v_pk_fma_f32 v[6:7], v[192:193], v[12:13], v[48:49] op_sel_hi:[1,0,1] neg_lo:[1,0,0] neg_hi:[1,0,0]
	v_pk_fma_f32 v[8:9], v[194:195], v[12:13], v[50:51] op_sel_hi:[1,0,1] neg_lo:[1,0,0] neg_hi:[1,0,0]
	v_pk_mul_f32 v[6:7], v[6:7], v[184:185]
	v_pk_mul_f32 v[8:9], v[8:9], v[186:187]
	s_waitcnt lgkmcnt(0)
	s_nop 0
	ds_read_b128 v[88:91], v10 offset:18688
	ds_read_b128 v[96:99], v10 offset:19200
	ds_read_b128 v[92:95], v10 offset:18944
	v_fma_mix_f32 v12, v6, v20, v180 op_sel_hi:[0,1,0]
	v_fma_mix_f32 v12, v7, v20, v12 op_sel:[0,1,0] op_sel_hi:[0,1,0]
	v_fma_mix_f32 v12, v8, v21, v12 op_sel_hi:[0,1,0]
	v_fma_mix_f32 v12, v9, v21, v12 op_sel:[0,1,0] op_sel_hi:[0,1,0]
	v_fma_mix_f32 v61, v6, v190, v180 op_sel_hi:[0,1,0]
	v_fma_mix_f32 v61, v7, v190, v61 op_sel:[0,1,0] op_sel_hi:[0,1,0]
	v_add_f32_dpp v12, v12, v12 row_ror:1 row_mask:0xf bank_mask:0xf bound_ctrl:1
	v_fma_mix_f32 v61, v8, v191, v61 op_sel_hi:[0,1,0]
	v_fma_mix_f32 v61, v9, v191, v61 op_sel:[0,1,0] op_sel_hi:[0,1,0]
	v_add_f32_dpp v12, v12, v12 row_ror:2 row_mask:0xf bank_mask:0xf bound_ctrl:1
	v_pk_fma_f32 v[48:49], v[28:29], v[66:67], v[6:7] op_sel_hi:[1,0,1]
	v_pk_fma_f32 v[50:51], v[30:31], v[66:67], v[8:9] op_sel_hi:[1,0,1]
	v_add_f32_dpp v12, v12, v12 row_ror:4 row_mask:0xf bank_mask:0xf bound_ctrl:1
	s_nop 1
	s_nop 0
	v_add_f32_dpp v12, v12, v12 row_ror:8 row_mask:0xf bank_mask:0xf bound_ctrl:1
	v_pk_fma_f32 v[6:7], v[24:25], v[12:13], v[48:49] op_sel_hi:[1,0,1] neg_lo:[1,0,0] neg_hi:[1,0,0]
	v_pk_fma_f32 v[8:9], v[26:27], v[12:13], v[50:51] op_sel_hi:[1,0,1] neg_lo:[1,0,0] neg_hi:[1,0,0]
	ds_read_b128 v[188:191], v10 offset:19712
	ds_read_b128 v[184:187], v10 offset:19456
	ds_read_b128 v[196:199], v10 offset:20224
	ds_read_b128 v[192:195], v10 offset:19968
	ds_read_b128 v[70:73], v11 offset:1280
	v_fma_mix_f32 v12, v6, v36, v180 op_sel_hi:[0,1,0]
	v_fma_mix_f32 v12, v7, v36, v12 op_sel:[0,1,0] op_sel_hi:[0,1,0]
	v_fma_mix_f32 v12, v8, v37, v12 op_sel_hi:[0,1,0]
	v_fma_mix_f32 v12, v9, v37, v12 op_sel:[0,1,0] op_sel_hi:[0,1,0]
	v_fma_mix_f32 v122, v6, v22, v180 op_sel_hi:[0,1,0]
	v_fma_mix_f32 v122, v7, v22, v122 op_sel:[0,1,0] op_sel_hi:[0,1,0]
	v_add_f32_dpp v12, v12, v12 row_ror:1 row_mask:0xf bank_mask:0xf bound_ctrl:1
	v_fma_mix_f32 v122, v8, v23, v122 op_sel_hi:[0,1,0]
	v_fma_mix_f32 v122, v9, v23, v122 op_sel:[0,1,0] op_sel_hi:[0,1,0]
	v_add_f32_dpp v12, v12, v12 row_ror:2 row_mask:0xf bank_mask:0xf bound_ctrl:1
	v_pk_fma_f32 v[48:49], v[44:45], v[66:67], v[6:7] op_sel:[0,1,0]
	v_pk_fma_f32 v[50:51], v[46:47], v[66:67], v[8:9] op_sel:[0,1,0]
	v_add_f32_dpp v12, v12, v12 row_ror:4 row_mask:0xf bank_mask:0xf bound_ctrl:1
	v_add_f32_dpp v83, v83, v83 row_ror:8 row_mask:0xf bank_mask:0xc
	v_add_f32_dpp v83, v52, v52 row_ror:8 row_mask:0xf bank_mask:0x3
	v_add_f32_dpp v100, v100, v100 row_ror:8 row_mask:0xf bank_mask:0xc
	v_add_f32_dpp v12, v12, v12 row_ror:8 row_mask:0xf bank_mask:0xf bound_ctrl:1
	v_pk_fma_f32 v[6:7], v[40:41], v[12:13], v[48:49] op_sel_hi:[1,0,1] neg_lo:[1,0,0] neg_hi:[1,0,0]
	v_pk_fma_f32 v[8:9], v[42:43], v[12:13], v[50:51] op_sel_hi:[1,0,1] neg_lo:[1,0,0] neg_hi:[1,0,0]
	s_waitcnt lgkmcnt(1)
	s_nop 0
	ds_read_b128 v[20:23], v10 offset:20736
	ds_read_b128 v[28:31], v10 offset:21248
	ds_read_b128 v[24:27], v10 offset:20992
	v_fma_mix_f32 v12, v6, v88, v180 op_sel_hi:[0,1,0]
	v_fma_mix_f32 v12, v7, v88, v12 op_sel:[0,1,0] op_sel_hi:[0,1,0]
	v_fma_mix_f32 v12, v8, v89, v12 op_sel_hi:[0,1,0]
	v_fma_mix_f32 v12, v9, v89, v12 op_sel:[0,1,0] op_sel_hi:[0,1,0]
	v_fma_mix_f32 v123, v6, v38, v180 op_sel_hi:[0,1,0]
	v_fma_mix_f32 v123, v7, v38, v123 op_sel:[0,1,0] op_sel_hi:[0,1,0]
	v_add_f32_dpp v12, v12, v12 row_ror:1 row_mask:0xf bank_mask:0xf bound_ctrl:1
	v_fma_mix_f32 v123, v8, v39, v123 op_sel_hi:[0,1,0]
	v_fma_mix_f32 v123, v9, v39, v123 op_sel:[0,1,0] op_sel_hi:[0,1,0]
	v_add_f32_dpp v12, v12, v12 row_ror:2 row_mask:0xf bank_mask:0xf bound_ctrl:1
	v_pk_fma_f32 v[48:49], v[96:97], v[68:69], v[6:7] op_sel_hi:[1,0,1]
	v_pk_fma_f32 v[50:51], v[98:99], v[68:69], v[8:9] op_sel_hi:[1,0,1]
	v_add_f32_dpp v12, v12, v12 row_ror:4 row_mask:0xf bank_mask:0xf bound_ctrl:1
	v_add_f32_dpp v100, v53, v53 row_ror:8 row_mask:0xf bank_mask:0x3
	v_add_f32_dpp v101, v101, v101 row_ror:8 row_mask:0xf bank_mask:0xc
	v_add_f32_dpp v101, v54, v54 row_ror:8 row_mask:0xf bank_mask:0x3
	v_add_f32_dpp v12, v12, v12 row_ror:8 row_mask:0xf bank_mask:0xf bound_ctrl:1
	v_pk_fma_f32 v[6:7], v[92:93], v[12:13], v[48:49] op_sel_hi:[1,0,1] neg_lo:[1,0,0] neg_hi:[1,0,0]
	v_pk_fma_f32 v[8:9], v[94:95], v[12:13], v[50:51] op_sel_hi:[1,0,1] neg_lo:[1,0,0] neg_hi:[1,0,0]
	ds_read_b128 v[36:39], v10 offset:21760
	ds_read_b128 v[44:47], v10 offset:22272
	ds_read_b128 v[40:43], v10 offset:22016
	v_fma_mix_f32 v12, v6, v188, v180 op_sel_hi:[0,1,0]
	v_fma_mix_f32 v12, v7, v188, v12 op_sel:[0,1,0] op_sel_hi:[0,1,0]
	v_fma_mix_f32 v12, v8, v189, v12 op_sel_hi:[0,1,0]
	v_fma_mix_f32 v12, v9, v189, v12 op_sel:[0,1,0] op_sel_hi:[0,1,0]
	v_fma_mix_f32 v124, v6, v90, v180 op_sel_hi:[0,1,0]
	v_fma_mix_f32 v124, v7, v90, v124 op_sel:[0,1,0] op_sel_hi:[0,1,0]
	v_add_f32_dpp v12, v12, v12 row_ror:1 row_mask:0xf bank_mask:0xf bound_ctrl:1
	v_fma_mix_f32 v124, v8, v91, v124 op_sel_hi:[0,1,0]
	v_fma_mix_f32 v124, v9, v91, v124 op_sel:[0,1,0] op_sel_hi:[0,1,0]
	v_add_f32_dpp v12, v12, v12 row_ror:2 row_mask:0xf bank_mask:0xf bound_ctrl:1
	v_pk_fma_f32 v[48:49], v[196:197], v[68:69], v[6:7] op_sel:[0,1,0]
	v_pk_fma_f32 v[50:51], v[198:199], v[68:69], v[8:9] op_sel:[0,1,0]
	v_add_f32_dpp v12, v12, v12 row_ror:4 row_mask:0xf bank_mask:0xf bound_ctrl:1
	v_add_f32_dpp v102, v102, v102 row_ror:8 row_mask:0xf bank_mask:0xc
	v_add_f32_dpp v102, v55, v55 row_ror:8 row_mask:0xf bank_mask:0x3
	v_add_f32_dpp v103, v103, v103 row_ror:8 row_mask:0xf bank_mask:0xc
	v_add_f32_dpp v12, v12, v12 row_ror:8 row_mask:0xf bank_mask:0xf bound_ctrl:1
	v_pk_fma_f32 v[6:7], v[192:193], v[12:13], v[48:49] op_sel_hi:[1,0,1] neg_lo:[1,0,0] neg_hi:[1,0,0]
	v_pk_fma_f32 v[8:9], v[194:195], v[12:13], v[50:51] op_sel_hi:[1,0,1] neg_lo:[1,0,0] neg_hi:[1,0,0]
	v_pk_mul_f32 v[6:7], v[6:7], v[184:185]
	v_pk_mul_f32 v[8:9], v[8:9], v[186:187]
	s_waitcnt lgkmcnt(0)
	s_nop 0
	ds_read_b128 v[88:91], v10 offset:22784
	ds_read_b128 v[96:99], v10 offset:23296
	ds_read_b128 v[92:95], v10 offset:23040
	v_fma_mix_f32 v12, v6, v20, v180 op_sel_hi:[0,1,0]
	v_fma_mix_f32 v12, v7, v20, v12 op_sel:[0,1,0] op_sel_hi:[0,1,0]
	v_fma_mix_f32 v12, v8, v21, v12 op_sel_hi:[0,1,0]
	v_fma_mix_f32 v12, v9, v21, v12 op_sel:[0,1,0] op_sel_hi:[0,1,0]
	v_fma_mix_f32 v125, v6, v190, v180 op_sel_hi:[0,1,0]
	v_fma_mix_f32 v125, v7, v190, v125 op_sel:[0,1,0] op_sel_hi:[0,1,0]
	v_add_f32_dpp v12, v12, v12 row_ror:1 row_mask:0xf bank_mask:0xf bound_ctrl:1
	v_fma_mix_f32 v125, v8, v191, v125 op_sel_hi:[0,1,0]
	v_fma_mix_f32 v125, v9, v191, v125 op_sel:[0,1,0] op_sel_hi:[0,1,0]
	v_add_f32_dpp v12, v12, v12 row_ror:2 row_mask:0xf bank_mask:0xf bound_ctrl:1
	v_pk_fma_f32 v[48:49], v[28:29], v[70:71], v[6:7] op_sel_hi:[1,0,1]
	v_pk_fma_f32 v[50:51], v[30:31], v[70:71], v[8:9] op_sel_hi:[1,0,1]
	v_add_f32_dpp v12, v12, v12 row_ror:4 row_mask:0xf bank_mask:0xf bound_ctrl:1
	v_add_f32_dpp v103, v56, v56 row_ror:8 row_mask:0xf bank_mask:0x3
	v_add_f32_dpp v104, v104, v104 row_ror:8 row_mask:0xf bank_mask:0xc
	v_add_f32_dpp v104, v57, v57 row_ror:8 row_mask:0xf bank_mask:0x3
	v_add_f32_dpp v12, v12, v12 row_ror:8 row_mask:0xf bank_mask:0xf bound_ctrl:1
	v_pk_fma_f32 v[6:7], v[24:25], v[12:13], v[48:49] op_sel_hi:[1,0,1] neg_lo:[1,0,0] neg_hi:[1,0,0]
	v_pk_fma_f32 v[8:9], v[26:27], v[12:13], v[50:51] op_sel_hi:[1,0,1] neg_lo:[1,0,0] neg_hi:[1,0,0]
	ds_read_b128 v[188:191], v10 offset:23808
	ds_read_b128 v[184:187], v10 offset:23552
	ds_read_b128 v[196:199], v10 offset:24320
	ds_read_b128 v[192:195], v10 offset:24064
	ds_read_b128 v[66:69], v11 offset:1536
	v_fma_mix_f32 v12, v6, v36, v180 op_sel_hi:[0,1,0]
	v_fma_mix_f32 v12, v7, v36, v12 op_sel:[0,1,0] op_sel_hi:[0,1,0]
	v_fma_mix_f32 v12, v8, v37, v12 op_sel_hi:[0,1,0]
	v_fma_mix_f32 v12, v9, v37, v12 op_sel:[0,1,0] op_sel_hi:[0,1,0]
	v_fma_mix_f32 v126, v6, v22, v180 op_sel_hi:[0,1,0]
	v_fma_mix_f32 v126, v7, v22, v126 op_sel:[0,1,0] op_sel_hi:[0,1,0]
	v_add_f32_dpp v12, v12, v12 row_ror:1 row_mask:0xf bank_mask:0xf bound_ctrl:1
	v_fma_mix_f32 v126, v8, v23, v126 op_sel_hi:[0,1,0]
	v_fma_mix_f32 v126, v9, v23, v126 op_sel:[0,1,0] op_sel_hi:[0,1,0]
	v_add_f32_dpp v12, v12, v12 row_ror:2 row_mask:0xf bank_mask:0xf bound_ctrl:1
	v_pk_fma_f32 v[48:49], v[44:45], v[70:71], v[6:7] op_sel:[0,1,0]
	v_pk_fma_f32 v[50:51], v[46:47], v[70:71], v[8:9] op_sel:[0,1,0]
	v_add_f32_dpp v12, v12, v12 row_ror:4 row_mask:0xf bank_mask:0xf bound_ctrl:1
	v_add_f32_dpp v105, v105, v105 row_ror:8 row_mask:0xf bank_mask:0xc
	v_add_f32_dpp v105, v81, v81 row_ror:8 row_mask:0xf bank_mask:0x3
	v_add_f32_dpp v12, v12, v12 row_ror:8 row_mask:0xf bank_mask:0xf bound_ctrl:1
	v_pk_fma_f32 v[6:7], v[40:41], v[12:13], v[48:49] op_sel_hi:[1,0,1] neg_lo:[1,0,0] neg_hi:[1,0,0]
	v_pk_fma_f32 v[8:9], v[42:43], v[12:13], v[50:51] op_sel_hi:[1,0,1] neg_lo:[1,0,0] neg_hi:[1,0,0]
	s_waitcnt lgkmcnt(1)
	s_nop 0
	ds_read_b128 v[20:23], v10 offset:24832
	ds_read_b128 v[28:31], v10 offset:25344
	ds_read_b128 v[24:27], v10 offset:25088
	v_fma_mix_f32 v12, v6, v88, v180 op_sel_hi:[0,1,0]
	v_fma_mix_f32 v12, v7, v88, v12 op_sel:[0,1,0] op_sel_hi:[0,1,0]
	v_fma_mix_f32 v12, v8, v89, v12 op_sel_hi:[0,1,0]
	v_fma_mix_f32 v12, v9, v89, v12 op_sel:[0,1,0] op_sel_hi:[0,1,0]
	v_fma_mix_f32 v127, v6, v38, v180 op_sel_hi:[0,1,0]
	v_fma_mix_f32 v127, v7, v38, v127 op_sel:[0,1,0] op_sel_hi:[0,1,0]
	v_add_f32_dpp v12, v12, v12 row_ror:1 row_mask:0xf bank_mask:0xf bound_ctrl:1
	v_fma_mix_f32 v127, v8, v39, v127 op_sel_hi:[0,1,0]
	v_fma_mix_f32 v127, v9, v39, v127 op_sel:[0,1,0] op_sel_hi:[0,1,0]
	v_add_f32_dpp v12, v12, v12 row_ror:2 row_mask:0xf bank_mask:0xf bound_ctrl:1
	v_pk_fma_f32 v[48:49], v[96:97], v[72:73], v[6:7] op_sel_hi:[1,0,1]
	v_pk_fma_f32 v[50:51], v[98:99], v[72:73], v[8:9] op_sel_hi:[1,0,1]
	v_add_f32_dpp v12, v12, v12 row_ror:4 row_mask:0xf bank_mask:0xf bound_ctrl:1
	v_add_f32_dpp v61, v61, v61 row_ror:8 row_mask:0xf bank_mask:0xc
	v_add_f32_dpp v61, v82, v82 row_ror:8 row_mask:0xf bank_mask:0x3
	v_add_f32_dpp v12, v12, v12 row_ror:8 row_mask:0xf bank_mask:0xf bound_ctrl:1
	v_pk_fma_f32 v[6:7], v[92:93], v[12:13], v[48:49] op_sel_hi:[1,0,1] neg_lo:[1,0,0] neg_hi:[1,0,0]
	v_pk_fma_f32 v[8:9], v[94:95], v[12:13], v[50:51] op_sel_hi:[1,0,1] neg_lo:[1,0,0] neg_hi:[1,0,0]
	ds_read_b128 v[36:39], v10 offset:25856
	ds_read_b128 v[44:47], v10 offset:26368
	ds_read_b128 v[40:43], v10 offset:26112
	v_fma_mix_f32 v12, v6, v188, v180 op_sel_hi:[0,1,0]
	v_fma_mix_f32 v12, v7, v188, v12 op_sel:[0,1,0] op_sel_hi:[0,1,0]
	v_fma_mix_f32 v12, v8, v189, v12 op_sel_hi:[0,1,0]
	v_fma_mix_f32 v12, v9, v189, v12 op_sel:[0,1,0] op_sel_hi:[0,1,0]
	v_fma_mix_f32 v128, v6, v90, v180 op_sel_hi:[0,1,0]
	v_fma_mix_f32 v128, v7, v90, v128 op_sel:[0,1,0] op_sel_hi:[0,1,0]
	v_add_f32_dpp v12, v12, v12 row_ror:1 row_mask:0xf bank_mask:0xf bound_ctrl:1
	v_fma_mix_f32 v128, v8, v91, v128 op_sel_hi:[0,1,0]
	v_fma_mix_f32 v128, v9, v91, v128 op_sel:[0,1,0] op_sel_hi:[0,1,0]
	v_add_f32_dpp v12, v12, v12 row_ror:2 row_mask:0xf bank_mask:0xf bound_ctrl:1
	v_pk_fma_f32 v[48:49], v[196:197], v[72:73], v[6:7] op_sel:[0,1,0]
	v_pk_fma_f32 v[50:51], v[198:199], v[72:73], v[8:9] op_sel:[0,1,0]
	v_add_f32_dpp v12, v12, v12 row_ror:4 row_mask:0xf bank_mask:0xf bound_ctrl:1
	v_add_f32_dpp v103, v103, v103 row_ror:4 row_mask:0xf bank_mask:0xa
	v_add_f32_dpp v103, v83, v83 row_ror:12 row_mask:0xf bank_mask:0x5
	v_add_f32_dpp v104, v104, v104 row_ror:4 row_mask:0xf bank_mask:0xa
	v_add_f32_dpp v12, v12, v12 row_ror:8 row_mask:0xf bank_mask:0xf bound_ctrl:1
	v_pk_fma_f32 v[6:7], v[192:193], v[12:13], v[48:49] op_sel_hi:[1,0,1] neg_lo:[1,0,0] neg_hi:[1,0,0]
	v_pk_fma_f32 v[8:9], v[194:195], v[12:13], v[50:51] op_sel_hi:[1,0,1] neg_lo:[1,0,0] neg_hi:[1,0,0]
	v_pk_mul_f32 v[6:7], v[6:7], v[184:185]
	v_pk_mul_f32 v[8:9], v[8:9], v[186:187]
	s_waitcnt lgkmcnt(0)
	s_nop 0
	ds_read_b128 v[88:91], v10 offset:26880
	ds_read_b128 v[96:99], v10 offset:27392
	ds_read_b128 v[92:95], v10 offset:27136
	v_fma_mix_f32 v12, v6, v20, v180 op_sel_hi:[0,1,0]
	v_fma_mix_f32 v12, v7, v20, v12 op_sel:[0,1,0] op_sel_hi:[0,1,0]
	v_fma_mix_f32 v12, v8, v21, v12 op_sel_hi:[0,1,0]
	v_fma_mix_f32 v12, v9, v21, v12 op_sel:[0,1,0] op_sel_hi:[0,1,0]
	v_fma_mix_f32 v129, v6, v190, v180 op_sel_hi:[0,1,0]
	v_fma_mix_f32 v129, v7, v190, v129 op_sel:[0,1,0] op_sel_hi:[0,1,0]
	v_add_f32_dpp v12, v12, v12 row_ror:1 row_mask:0xf bank_mask:0xf bound_ctrl:1
	v_fma_mix_f32 v129, v8, v191, v129 op_sel_hi:[0,1,0]
	v_fma_mix_f32 v129, v9, v191, v129 op_sel:[0,1,0] op_sel_hi:[0,1,0]
	v_add_f32_dpp v12, v12, v12 row_ror:2 row_mask:0xf bank_mask:0xf bound_ctrl:1
	v_pk_fma_f32 v[48:49], v[28:29], v[66:67], v[6:7] op_sel_hi:[1,0,1]
	v_pk_fma_f32 v[50:51], v[30:31], v[66:67], v[8:9] op_sel_hi:[1,0,1]
	v_add_f32_dpp v12, v12, v12 row_ror:4 row_mask:0xf bank_mask:0xf bound_ctrl:1
	v_add_f32_dpp v104, v100, v100 row_ror:12 row_mask:0xf bank_mask:0x5
	v_add_f32_dpp v105, v105, v105 row_ror:4 row_mask:0xf bank_mask:0xa
	v_add_f32_dpp v105, v101, v101 row_ror:12 row_mask:0xf bank_mask:0x5
	v_add_f32_dpp v12, v12, v12 row_ror:8 row_mask:0xf bank_mask:0xf bound_ctrl:1
	v_pk_fma_f32 v[6:7], v[24:25], v[12:13], v[48:49] op_sel_hi:[1,0,1] neg_lo:[1,0,0] neg_hi:[1,0,0]
	v_pk_fma_f32 v[8:9], v[26:27], v[12:13], v[50:51] op_sel_hi:[1,0,1] neg_lo:[1,0,0] neg_hi:[1,0,0]
	ds_read_b128 v[188:191], v10 offset:27904
	ds_read_b128 v[184:187], v10 offset:27648
	ds_read_b128 v[196:199], v10 offset:28416
	ds_read_b128 v[192:195], v10 offset:28160
	ds_read_b128 v[70:73], v11 offset:1792
	v_fma_mix_f32 v12, v6, v36, v180 op_sel_hi:[0,1,0]
	v_fma_mix_f32 v12, v7, v36, v12 op_sel:[0,1,0] op_sel_hi:[0,1,0]
	v_fma_mix_f32 v12, v8, v37, v12 op_sel_hi:[0,1,0]
	v_fma_mix_f32 v12, v9, v37, v12 op_sel:[0,1,0] op_sel_hi:[0,1,0]
	v_fma_mix_f32 v130, v6, v22, v180 op_sel_hi:[0,1,0]
	v_fma_mix_f32 v130, v7, v22, v130 op_sel:[0,1,0] op_sel_hi:[0,1,0]
	v_add_f32_dpp v12, v12, v12 row_ror:1 row_mask:0xf bank_mask:0xf bound_ctrl:1
	v_fma_mix_f32 v130, v8, v23, v130 op_sel_hi:[0,1,0]
	v_fma_mix_f32 v130, v9, v23, v130 op_sel:[0,1,0] op_sel_hi:[0,1,0]
	v_add_f32_dpp v12, v12, v12 row_ror:2 row_mask:0xf bank_mask:0xf bound_ctrl:1
	v_pk_fma_f32 v[48:49], v[44:45], v[66:67], v[6:7] op_sel:[0,1,0]
	v_pk_fma_f32 v[50:51], v[46:47], v[66:67], v[8:9] op_sel:[0,1,0]
	v_add_f32_dpp v12, v12, v12 row_ror:4 row_mask:0xf bank_mask:0xf bound_ctrl:1
	v_add_f32_dpp v61, v61, v61 row_ror:4 row_mask:0xf bank_mask:0xa
	v_add_f32_dpp v61, v102, v102 row_ror:12 row_mask:0xf bank_mask:0x5
	v_add_f32_dpp v12, v12, v12 row_ror:8 row_mask:0xf bank_mask:0xf bound_ctrl:1
	v_pk_fma_f32 v[6:7], v[40:41], v[12:13], v[48:49] op_sel_hi:[1,0,1] neg_lo:[1,0,0] neg_hi:[1,0,0]
	v_pk_fma_f32 v[8:9], v[42:43], v[12:13], v[50:51] op_sel_hi:[1,0,1] neg_lo:[1,0,0] neg_hi:[1,0,0]
	s_waitcnt lgkmcnt(1)
	s_nop 0
	ds_read_b128 v[20:23], v10 offset:28928
	ds_read_b128 v[28:31], v10 offset:29440
	ds_read_b128 v[24:27], v10 offset:29184
	v_fma_mix_f32 v12, v6, v88, v180 op_sel_hi:[0,1,0]
	v_fma_mix_f32 v12, v7, v88, v12 op_sel:[0,1,0] op_sel_hi:[0,1,0]
	v_fma_mix_f32 v12, v8, v89, v12 op_sel_hi:[0,1,0]
	v_fma_mix_f32 v12, v9, v89, v12 op_sel:[0,1,0] op_sel_hi:[0,1,0]
	v_fma_mix_f32 v131, v6, v38, v180 op_sel_hi:[0,1,0]
	v_fma_mix_f32 v131, v7, v38, v131 op_sel:[0,1,0] op_sel_hi:[0,1,0]
	v_add_f32_dpp v12, v12, v12 row_ror:1 row_mask:0xf bank_mask:0xf bound_ctrl:1
	v_fma_mix_f32 v131, v8, v39, v131 op_sel_hi:[0,1,0]
	v_fma_mix_f32 v131, v9, v39, v131 op_sel:[0,1,0] op_sel_hi:[0,1,0]
	v_add_f32_dpp v12, v12, v12 row_ror:2 row_mask:0xf bank_mask:0xf bound_ctrl:1
	v_pk_fma_f32 v[48:49], v[96:97], v[68:69], v[6:7] op_sel_hi:[1,0,1]
	v_pk_fma_f32 v[50:51], v[98:99], v[68:69], v[8:9] op_sel_hi:[1,0,1]
	v_add_f32_dpp v12, v12, v12 row_ror:4 row_mask:0xf bank_mask:0xf bound_ctrl:1
	v_cndmask_b32_e64 v62, v105, v103, s[38:39]
	v_cndmask_b32_e64 v63, v103, v105, s[38:39]
	v_add_f32_dpp v12, v12, v12 row_ror:8 row_mask:0xf bank_mask:0xf bound_ctrl:1
	v_pk_fma_f32 v[6:7], v[92:93], v[12:13], v[48:49] op_sel_hi:[1,0,1] neg_lo:[1,0,0] neg_hi:[1,0,0]
	v_pk_fma_f32 v[8:9], v[94:95], v[12:13], v[50:51] op_sel_hi:[1,0,1] neg_lo:[1,0,0] neg_hi:[1,0,0]
	ds_read_b128 v[36:39], v10 offset:29952
	ds_read_b128 v[44:47], v10 offset:30464
	ds_read_b128 v[40:43], v10 offset:30208
	v_fma_mix_f32 v12, v6, v188, v180 op_sel_hi:[0,1,0]
	v_fma_mix_f32 v12, v7, v188, v12 op_sel:[0,1,0] op_sel_hi:[0,1,0]
	v_fma_mix_f32 v12, v8, v189, v12 op_sel_hi:[0,1,0]
	v_fma_mix_f32 v12, v9, v189, v12 op_sel:[0,1,0] op_sel_hi:[0,1,0]
	v_fma_mix_f32 v132, v6, v90, v180 op_sel_hi:[0,1,0]
	v_fma_mix_f32 v132, v7, v90, v132 op_sel:[0,1,0] op_sel_hi:[0,1,0]
	v_add_f32_dpp v12, v12, v12 row_ror:1 row_mask:0xf bank_mask:0xf bound_ctrl:1
	v_fma_mix_f32 v132, v8, v91, v132 op_sel_hi:[0,1,0]
	v_fma_mix_f32 v132, v9, v91, v132 op_sel:[0,1,0] op_sel_hi:[0,1,0]
	v_add_f32_dpp v12, v12, v12 row_ror:2 row_mask:0xf bank_mask:0xf bound_ctrl:1
	v_pk_fma_f32 v[48:49], v[196:197], v[68:69], v[6:7] op_sel:[0,1,0]
	v_pk_fma_f32 v[50:51], v[198:199], v[68:69], v[8:9] op_sel:[0,1,0]
	v_add_f32_dpp v12, v12, v12 row_ror:4 row_mask:0xf bank_mask:0xf bound_ctrl:1
	v_cndmask_b32_e64 v64, v61, v104, s[38:39]
	v_cndmask_b32_e64 v65, v104, v61, s[38:39]
	v_add_f32_dpp v12, v12, v12 row_ror:8 row_mask:0xf bank_mask:0xf bound_ctrl:1
	v_pk_fma_f32 v[6:7], v[192:193], v[12:13], v[48:49] op_sel_hi:[1,0,1] neg_lo:[1,0,0] neg_hi:[1,0,0]
	v_pk_fma_f32 v[8:9], v[194:195], v[12:13], v[50:51] op_sel_hi:[1,0,1] neg_lo:[1,0,0] neg_hi:[1,0,0]
	v_pk_mul_f32 v[6:7], v[6:7], v[184:185]
	v_pk_mul_f32 v[8:9], v[8:9], v[186:187]
	s_waitcnt lgkmcnt(0)
	s_nop 0
	ds_read_b128 v[88:91], v10 offset:30976
	ds_read_b128 v[96:99], v10 offset:31488
	ds_read_b128 v[92:95], v10 offset:31232
	v_fma_mix_f32 v12, v6, v20, v180 op_sel_hi:[0,1,0]
	v_fma_mix_f32 v12, v7, v20, v12 op_sel:[0,1,0] op_sel_hi:[0,1,0]
	v_fma_mix_f32 v12, v8, v21, v12 op_sel_hi:[0,1,0]
	v_fma_mix_f32 v12, v9, v21, v12 op_sel:[0,1,0] op_sel_hi:[0,1,0]
	v_fma_mix_f32 v133, v6, v190, v180 op_sel_hi:[0,1,0]
	v_fma_mix_f32 v133, v7, v190, v133 op_sel:[0,1,0] op_sel_hi:[0,1,0]
	v_add_f32_dpp v12, v12, v12 row_ror:1 row_mask:0xf bank_mask:0xf bound_ctrl:1
	v_fma_mix_f32 v133, v8, v191, v133 op_sel_hi:[0,1,0]
	v_fma_mix_f32 v133, v9, v191, v133 op_sel:[0,1,0] op_sel_hi:[0,1,0]
	v_add_f32_dpp v12, v12, v12 row_ror:2 row_mask:0xf bank_mask:0xf bound_ctrl:1
	v_pk_fma_f32 v[48:49], v[28:29], v[70:71], v[6:7] op_sel_hi:[1,0,1]
	v_pk_fma_f32 v[50:51], v[30:31], v[70:71], v[8:9] op_sel_hi:[1,0,1]
	v_add_f32_dpp v12, v12, v12 row_ror:4 row_mask:0xf bank_mask:0xf bound_ctrl:1
	v_add_f32_dpp v62, v63, v62 quad_perm:[2,3,0,1] row_mask:0xf bank_mask:0xf bound_ctrl:1
	v_add_f32_dpp v63, v65, v64 quad_perm:[2,3,0,1] row_mask:0xf bank_mask:0xf bound_ctrl:1
	v_add_f32_dpp v12, v12, v12 row_ror:8 row_mask:0xf bank_mask:0xf bound_ctrl:1
	v_pk_fma_f32 v[6:7], v[24:25], v[12:13], v[48:49] op_sel_hi:[1,0,1] neg_lo:[1,0,0] neg_hi:[1,0,0]
	v_pk_fma_f32 v[8:9], v[26:27], v[12:13], v[50:51] op_sel_hi:[1,0,1] neg_lo:[1,0,0] neg_hi:[1,0,0]
	ds_read_b128 v[188:191], v10 offset:32000
	ds_read_b128 v[184:187], v10 offset:31744
	ds_read_b128 v[196:199], v10 offset:32512
	ds_read_b128 v[192:195], v10 offset:32256
	ds_read_b128 v[66:69], v11 offset:2048
	v_fma_mix_f32 v12, v6, v36, v180 op_sel_hi:[0,1,0]
	v_fma_mix_f32 v12, v7, v36, v12 op_sel:[0,1,0] op_sel_hi:[0,1,0]
	v_fma_mix_f32 v12, v8, v37, v12 op_sel_hi:[0,1,0]
	v_fma_mix_f32 v12, v9, v37, v12 op_sel:[0,1,0] op_sel_hi:[0,1,0]
	v_fma_mix_f32 v134, v6, v22, v180 op_sel_hi:[0,1,0]
	v_fma_mix_f32 v134, v7, v22, v134 op_sel:[0,1,0] op_sel_hi:[0,1,0]
	v_add_f32_dpp v12, v12, v12 row_ror:1 row_mask:0xf bank_mask:0xf bound_ctrl:1
	v_fma_mix_f32 v134, v8, v23, v134 op_sel_hi:[0,1,0]
	v_fma_mix_f32 v134, v9, v23, v134 op_sel:[0,1,0] op_sel_hi:[0,1,0]
	v_add_f32_dpp v12, v12, v12 row_ror:2 row_mask:0xf bank_mask:0xf bound_ctrl:1
	v_pk_fma_f32 v[48:49], v[44:45], v[70:71], v[6:7] op_sel:[0,1,0]
	v_pk_fma_f32 v[50:51], v[46:47], v[70:71], v[8:9] op_sel:[0,1,0]
	v_add_f32_dpp v12, v12, v12 row_ror:4 row_mask:0xf bank_mask:0xf bound_ctrl:1
	v_cndmask_b32_e64 v65, v63, v62, s[40:41]
	v_cndmask_b32_e64 v62, v62, v63, s[40:41]
	v_add_f32_dpp v12, v12, v12 row_ror:8 row_mask:0xf bank_mask:0xf bound_ctrl:1
	v_pk_fma_f32 v[6:7], v[40:41], v[12:13], v[48:49] op_sel_hi:[1,0,1] neg_lo:[1,0,0] neg_hi:[1,0,0]
	v_pk_fma_f32 v[8:9], v[42:43], v[12:13], v[50:51] op_sel_hi:[1,0,1] neg_lo:[1,0,0] neg_hi:[1,0,0]
	s_waitcnt lgkmcnt(1)
	s_nop 0
	ds_read_b128 v[20:23], v10 offset:33024
	ds_read_b128 v[28:31], v10 offset:33536
	ds_read_b128 v[24:27], v10 offset:33280
	v_fma_mix_f32 v12, v6, v88, v180 op_sel_hi:[0,1,0]
	v_fma_mix_f32 v12, v7, v88, v12 op_sel:[0,1,0] op_sel_hi:[0,1,0]
	v_fma_mix_f32 v12, v8, v89, v12 op_sel_hi:[0,1,0]
	v_fma_mix_f32 v12, v9, v89, v12 op_sel:[0,1,0] op_sel_hi:[0,1,0]
	v_fma_mix_f32 v135, v6, v38, v180 op_sel_hi:[0,1,0]
	v_fma_mix_f32 v135, v7, v38, v135 op_sel:[0,1,0] op_sel_hi:[0,1,0]
	v_add_f32_dpp v12, v12, v12 row_ror:1 row_mask:0xf bank_mask:0xf bound_ctrl:1
	v_fma_mix_f32 v135, v8, v39, v135 op_sel_hi:[0,1,0]
	v_fma_mix_f32 v135, v9, v39, v135 op_sel:[0,1,0] op_sel_hi:[0,1,0]
	v_add_f32_dpp v12, v12, v12 row_ror:2 row_mask:0xf bank_mask:0xf bound_ctrl:1
	v_pk_fma_f32 v[48:49], v[96:97], v[72:73], v[6:7] op_sel_hi:[1,0,1]
	v_pk_fma_f32 v[50:51], v[98:99], v[72:73], v[8:9] op_sel_hi:[1,0,1]
	v_add_f32_dpp v12, v12, v12 row_ror:4 row_mask:0xf bank_mask:0xf bound_ctrl:1
	v_add_f32_dpp v62, v62, v65 quad_perm:[1,0,3,2] row_mask:0xf bank_mask:0xf bound_ctrl:1
	v_cvt_pk_bf16_f32 v62, v62, v62
	v_add_f32_dpp v12, v12, v12 row_ror:8 row_mask:0xf bank_mask:0xf bound_ctrl:1
	v_pk_fma_f32 v[6:7], v[92:93], v[12:13], v[48:49] op_sel_hi:[1,0,1] neg_lo:[1,0,0] neg_hi:[1,0,0]
	v_pk_fma_f32 v[8:9], v[94:95], v[12:13], v[50:51] op_sel_hi:[1,0,1] neg_lo:[1,0,0] neg_hi:[1,0,0]
	ds_read_b128 v[36:39], v10 offset:34048
	ds_read_b128 v[44:47], v10 offset:34560
	ds_read_b128 v[40:43], v10 offset:34304
	v_fma_mix_f32 v12, v6, v188, v180 op_sel_hi:[0,1,0]
	v_fma_mix_f32 v12, v7, v188, v12 op_sel:[0,1,0] op_sel_hi:[0,1,0]
	v_fma_mix_f32 v12, v8, v189, v12 op_sel_hi:[0,1,0]
	v_fma_mix_f32 v12, v9, v189, v12 op_sel:[0,1,0] op_sel_hi:[0,1,0]
	v_fma_mix_f32 v136, v6, v90, v180 op_sel_hi:[0,1,0]
	v_fma_mix_f32 v136, v7, v90, v136 op_sel:[0,1,0] op_sel_hi:[0,1,0]
	v_add_f32_dpp v12, v12, v12 row_ror:1 row_mask:0xf bank_mask:0xf bound_ctrl:1
	v_fma_mix_f32 v136, v8, v91, v136 op_sel_hi:[0,1,0]
	v_fma_mix_f32 v136, v9, v91, v136 op_sel:[0,1,0] op_sel_hi:[0,1,0]
	v_add_f32_dpp v12, v12, v12 row_ror:2 row_mask:0xf bank_mask:0xf bound_ctrl:1
	v_pk_fma_f32 v[48:49], v[196:197], v[72:73], v[6:7] op_sel:[0,1,0]
	v_pk_fma_f32 v[50:51], v[198:199], v[72:73], v[8:9] op_sel:[0,1,0]
	v_add_f32_dpp v12, v12, v12 row_ror:4 row_mask:0xf bank_mask:0xf bound_ctrl:1
	global_store_short v[2:3], v62, off
	v_lshl_add_u64 v[2:3], v[2:3], 0, s[84:85]
	v_add_f32_dpp v12, v12, v12 row_ror:8 row_mask:0xf bank_mask:0xf bound_ctrl:1
	v_pk_fma_f32 v[6:7], v[192:193], v[12:13], v[48:49] op_sel_hi:[1,0,1] neg_lo:[1,0,0] neg_hi:[1,0,0]
	v_pk_fma_f32 v[8:9], v[194:195], v[12:13], v[50:51] op_sel_hi:[1,0,1] neg_lo:[1,0,0] neg_hi:[1,0,0]
	v_pk_mul_f32 v[6:7], v[6:7], v[184:185]
	v_pk_mul_f32 v[8:9], v[8:9], v[186:187]
	s_waitcnt lgkmcnt(0)
	s_nop 0
	ds_read_b128 v[88:91], v10 offset:35072
	ds_read_b128 v[96:99], v10 offset:35584
	ds_read_b128 v[92:95], v10 offset:35328
	v_fma_mix_f32 v12, v6, v20, v180 op_sel_hi:[0,1,0]
	v_fma_mix_f32 v12, v7, v20, v12 op_sel:[0,1,0] op_sel_hi:[0,1,0]
	v_fma_mix_f32 v12, v8, v21, v12 op_sel_hi:[0,1,0]
	v_fma_mix_f32 v12, v9, v21, v12 op_sel:[0,1,0] op_sel_hi:[0,1,0]
	v_fma_mix_f32 v137, v6, v190, v180 op_sel_hi:[0,1,0]
	v_fma_mix_f32 v137, v7, v190, v137 op_sel:[0,1,0] op_sel_hi:[0,1,0]
	v_add_f32_dpp v12, v12, v12 row_ror:1 row_mask:0xf bank_mask:0xf bound_ctrl:1
	v_fma_mix_f32 v137, v8, v191, v137 op_sel_hi:[0,1,0]
	v_fma_mix_f32 v137, v9, v191, v137 op_sel:[0,1,0] op_sel_hi:[0,1,0]
	v_add_f32_dpp v12, v12, v12 row_ror:2 row_mask:0xf bank_mask:0xf bound_ctrl:1
	v_pk_fma_f32 v[48:49], v[28:29], v[66:67], v[6:7] op_sel_hi:[1,0,1]
	v_pk_fma_f32 v[50:51], v[30:31], v[66:67], v[8:9] op_sel_hi:[1,0,1]
	v_add_f32_dpp v12, v12, v12 row_ror:4 row_mask:0xf bank_mask:0xf bound_ctrl:1
	s_nop 1
	s_nop 0
	v_add_f32_dpp v12, v12, v12 row_ror:8 row_mask:0xf bank_mask:0xf bound_ctrl:1
	v_pk_fma_f32 v[6:7], v[24:25], v[12:13], v[48:49] op_sel_hi:[1,0,1] neg_lo:[1,0,0] neg_hi:[1,0,0]
	v_pk_fma_f32 v[8:9], v[26:27], v[12:13], v[50:51] op_sel_hi:[1,0,1] neg_lo:[1,0,0] neg_hi:[1,0,0]
	ds_read_b128 v[188:191], v10 offset:36096
	ds_read_b128 v[184:187], v10 offset:35840
	ds_read_b128 v[196:199], v10 offset:36608
	ds_read_b128 v[192:195], v10 offset:36352
	ds_read_b128 v[70:73], v11 offset:2304
	v_fma_mix_f32 v12, v6, v36, v180 op_sel_hi:[0,1,0]
	v_fma_mix_f32 v12, v7, v36, v12 op_sel:[0,1,0] op_sel_hi:[0,1,0]
	v_fma_mix_f32 v12, v8, v37, v12 op_sel_hi:[0,1,0]
	v_fma_mix_f32 v12, v9, v37, v12 op_sel:[0,1,0] op_sel_hi:[0,1,0]
	v_fma_mix_f32 v52, v6, v22, v180 op_sel_hi:[0,1,0]
	v_fma_mix_f32 v52, v7, v22, v52 op_sel:[0,1,0] op_sel_hi:[0,1,0]
	v_add_f32_dpp v12, v12, v12 row_ror:1 row_mask:0xf bank_mask:0xf bound_ctrl:1
	v_fma_mix_f32 v52, v8, v23, v52 op_sel_hi:[0,1,0]
	v_fma_mix_f32 v52, v9, v23, v52 op_sel:[0,1,0] op_sel_hi:[0,1,0]
	v_add_f32_dpp v12, v12, v12 row_ror:2 row_mask:0xf bank_mask:0xf bound_ctrl:1
	v_pk_fma_f32 v[48:49], v[44:45], v[66:67], v[6:7] op_sel:[0,1,0]
	v_pk_fma_f32 v[50:51], v[46:47], v[66:67], v[8:9] op_sel:[0,1,0]
	v_add_f32_dpp v12, v12, v12 row_ror:4 row_mask:0xf bank_mask:0xf bound_ctrl:1
	v_add_f32_dpp v130, v130, v130 row_ror:8 row_mask:0xf bank_mask:0xc
	v_add_f32_dpp v130, v122, v122 row_ror:8 row_mask:0xf bank_mask:0x3
	v_add_f32_dpp v131, v131, v131 row_ror:8 row_mask:0xf bank_mask:0xc
	v_add_f32_dpp v12, v12, v12 row_ror:8 row_mask:0xf bank_mask:0xf bound_ctrl:1
	v_pk_fma_f32 v[6:7], v[40:41], v[12:13], v[48:49] op_sel_hi:[1,0,1] neg_lo:[1,0,0] neg_hi:[1,0,0]
	v_pk_fma_f32 v[8:9], v[42:43], v[12:13], v[50:51] op_sel_hi:[1,0,1] neg_lo:[1,0,0] neg_hi:[1,0,0]
	s_waitcnt lgkmcnt(1)
	s_nop 0
	ds_read_b128 v[20:23], v10 offset:37120
	ds_read_b128 v[28:31], v10 offset:37632
	ds_read_b128 v[24:27], v10 offset:37376
	v_fma_mix_f32 v12, v6, v88, v180 op_sel_hi:[0,1,0]
	v_fma_mix_f32 v12, v7, v88, v12 op_sel:[0,1,0] op_sel_hi:[0,1,0]
	v_fma_mix_f32 v12, v8, v89, v12 op_sel_hi:[0,1,0]
	v_fma_mix_f32 v12, v9, v89, v12 op_sel:[0,1,0] op_sel_hi:[0,1,0]
	v_fma_mix_f32 v53, v6, v38, v180 op_sel_hi:[0,1,0]
	v_fma_mix_f32 v53, v7, v38, v53 op_sel:[0,1,0] op_sel_hi:[0,1,0]
	v_add_f32_dpp v12, v12, v12 row_ror:1 row_mask:0xf bank_mask:0xf bound_ctrl:1
	v_fma_mix_f32 v53, v8, v39, v53 op_sel_hi:[0,1,0]
	v_fma_mix_f32 v53, v9, v39, v53 op_sel:[0,1,0] op_sel_hi:[0,1,0]
	v_add_f32_dpp v12, v12, v12 row_ror:2 row_mask:0xf bank_mask:0xf bound_ctrl:1
	v_pk_fma_f32 v[48:49], v[96:97], v[68:69], v[6:7] op_sel_hi:[1,0,1]
	v_pk_fma_f32 v[50:51], v[98:99], v[68:69], v[8:9] op_sel_hi:[1,0,1]
	v_add_f32_dpp v12, v12, v12 row_ror:4 row_mask:0xf bank_mask:0xf bound_ctrl:1
	v_add_f32_dpp v131, v123, v123 row_ror:8 row_mask:0xf bank_mask:0x3
	v_add_f32_dpp v132, v132, v132 row_ror:8 row_mask:0xf bank_mask:0xc
	v_add_f32_dpp v132, v124, v124 row_ror:8 row_mask:0xf bank_mask:0x3
	v_add_f32_dpp v12, v12, v12 row_ror:8 row_mask:0xf bank_mask:0xf bound_ctrl:1
	v_pk_fma_f32 v[6:7], v[92:93], v[12:13], v[48:49] op_sel_hi:[1,0,1] neg_lo:[1,0,0] neg_hi:[1,0,0]
	v_pk_fma_f32 v[8:9], v[94:95], v[12:13], v[50:51] op_sel_hi:[1,0,1] neg_lo:[1,0,0] neg_hi:[1,0,0]
	ds_read_b128 v[36:39], v10 offset:38144
	ds_read_b128 v[44:47], v10 offset:38656
	ds_read_b128 v[40:43], v10 offset:38400
	v_fma_mix_f32 v12, v6, v188, v180 op_sel_hi:[0,1,0]
	v_fma_mix_f32 v12, v7, v188, v12 op_sel:[0,1,0] op_sel_hi:[0,1,0]
	v_fma_mix_f32 v12, v8, v189, v12 op_sel_hi:[0,1,0]
	v_fma_mix_f32 v12, v9, v189, v12 op_sel:[0,1,0] op_sel_hi:[0,1,0]
	v_fma_mix_f32 v54, v6, v90, v180 op_sel_hi:[0,1,0]
	v_fma_mix_f32 v54, v7, v90, v54 op_sel:[0,1,0] op_sel_hi:[0,1,0]
	v_add_f32_dpp v12, v12, v12 row_ror:1 row_mask:0xf bank_mask:0xf bound_ctrl:1
	v_fma_mix_f32 v54, v8, v91, v54 op_sel_hi:[0,1,0]
	v_fma_mix_f32 v54, v9, v91, v54 op_sel:[0,1,0] op_sel_hi:[0,1,0]
	v_add_f32_dpp v12, v12, v12 row_ror:2 row_mask:0xf bank_mask:0xf bound_ctrl:1
	v_pk_fma_f32 v[48:49], v[196:197], v[68:69], v[6:7] op_sel:[0,1,0]
	v_pk_fma_f32 v[50:51], v[198:199], v[68:69], v[8:9] op_sel:[0,1,0]
	v_add_f32_dpp v12, v12, v12 row_ror:4 row_mask:0xf bank_mask:0xf bound_ctrl:1
	v_add_f32_dpp v133, v133, v133 row_ror:8 row_mask:0xf bank_mask:0xc
	v_add_f32_dpp v133, v125, v125 row_ror:8 row_mask:0xf bank_mask:0x3
	v_add_f32_dpp v134, v134, v134 row_ror:8 row_mask:0xf bank_mask:0xc
	v_add_f32_dpp v12, v12, v12 row_ror:8 row_mask:0xf bank_mask:0xf bound_ctrl:1
	v_pk_fma_f32 v[6:7], v[192:193], v[12:13], v[48:49] op_sel_hi:[1,0,1] neg_lo:[1,0,0] neg_hi:[1,0,0]
	v_pk_fma_f32 v[8:9], v[194:195], v[12:13], v[50:51] op_sel_hi:[1,0,1] neg_lo:[1,0,0] neg_hi:[1,0,0]
	v_pk_mul_f32 v[6:7], v[6:7], v[184:185]
	v_pk_mul_f32 v[8:9], v[8:9], v[186:187]
	s_waitcnt lgkmcnt(0)
	s_nop 0
	ds_read_b128 v[88:91], v10 offset:39168
	ds_read_b128 v[96:99], v10 offset:39680
	ds_read_b128 v[92:95], v10 offset:39424
	v_fma_mix_f32 v12, v6, v20, v180 op_sel_hi:[0,1,0]
	v_fma_mix_f32 v12, v7, v20, v12 op_sel:[0,1,0] op_sel_hi:[0,1,0]
	v_fma_mix_f32 v12, v8, v21, v12 op_sel_hi:[0,1,0]
	v_fma_mix_f32 v12, v9, v21, v12 op_sel:[0,1,0] op_sel_hi:[0,1,0]
	v_fma_mix_f32 v55, v6, v190, v180 op_sel_hi:[0,1,0]
	v_fma_mix_f32 v55, v7, v190, v55 op_sel:[0,1,0] op_sel_hi:[0,1,0]
	v_add_f32_dpp v12, v12, v12 row_ror:1 row_mask:0xf bank_mask:0xf bound_ctrl:1
	v_fma_mix_f32 v55, v8, v191, v55 op_sel_hi:[0,1,0]
	v_fma_mix_f32 v55, v9, v191, v55 op_sel:[0,1,0] op_sel_hi:[0,1,0]
	v_add_f32_dpp v12, v12, v12 row_ror:2 row_mask:0xf bank_mask:0xf bound_ctrl:1
	v_pk_fma_f32 v[48:49], v[28:29], v[70:71], v[6:7] op_sel_hi:[1,0,1]
	v_pk_fma_f32 v[50:51], v[30:31], v[70:71], v[8:9] op_sel_hi:[1,0,1]
	v_add_f32_dpp v12, v12, v12 row_ror:4 row_mask:0xf bank_mask:0xf bound_ctrl:1
	v_add_f32_dpp v134, v126, v126 row_ror:8 row_mask:0xf bank_mask:0x3
	v_add_f32_dpp v135, v135, v135 row_ror:8 row_mask:0xf bank_mask:0xc
	v_add_f32_dpp v135, v127, v127 row_ror:8 row_mask:0xf bank_mask:0x3
	v_add_f32_dpp v12, v12, v12 row_ror:8 row_mask:0xf bank_mask:0xf bound_ctrl:1
	v_pk_fma_f32 v[6:7], v[24:25], v[12:13], v[48:49] op_sel_hi:[1,0,1] neg_lo:[1,0,0] neg_hi:[1,0,0]
	v_pk_fma_f32 v[8:9], v[26:27], v[12:13], v[50:51] op_sel_hi:[1,0,1] neg_lo:[1,0,0] neg_hi:[1,0,0]
	ds_read_b128 v[188:191], v10 offset:40192
	ds_read_b128 v[184:187], v10 offset:39936
	ds_read_b128 v[196:199], v10 offset:40704
	ds_read_b128 v[192:195], v10 offset:40448
	ds_read_b128 v[66:69], v11 offset:2560
	v_fma_mix_f32 v12, v6, v36, v180 op_sel_hi:[0,1,0]
	v_fma_mix_f32 v12, v7, v36, v12 op_sel:[0,1,0] op_sel_hi:[0,1,0]
	v_fma_mix_f32 v12, v8, v37, v12 op_sel_hi:[0,1,0]
	v_fma_mix_f32 v12, v9, v37, v12 op_sel:[0,1,0] op_sel_hi:[0,1,0]
	v_fma_mix_f32 v56, v6, v22, v180 op_sel_hi:[0,1,0]
	v_fma_mix_f32 v56, v7, v22, v56 op_sel:[0,1,0] op_sel_hi:[0,1,0]
	v_add_f32_dpp v12, v12, v12 row_ror:1 row_mask:0xf bank_mask:0xf bound_ctrl:1
	v_fma_mix_f32 v56, v8, v23, v56 op_sel_hi:[0,1,0]
	v_fma_mix_f32 v56, v9, v23, v56 op_sel:[0,1,0] op_sel_hi:[0,1,0]
	v_add_f32_dpp v12, v12, v12 row_ror:2 row_mask:0xf bank_mask:0xf bound_ctrl:1
	v_pk_fma_f32 v[48:49], v[44:45], v[70:71], v[6:7] op_sel:[0,1,0]
	v_pk_fma_f32 v[50:51], v[46:47], v[70:71], v[8:9] op_sel:[0,1,0]
	v_add_f32_dpp v12, v12, v12 row_ror:4 row_mask:0xf bank_mask:0xf bound_ctrl:1
	v_add_f32_dpp v136, v136, v136 row_ror:8 row_mask:0xf bank_mask:0xc
	v_add_f32_dpp v136, v128, v128 row_ror:8 row_mask:0xf bank_mask:0x3
	v_add_f32_dpp v12, v12, v12 row_ror:8 row_mask:0xf bank_mask:0xf bound_ctrl:1
	v_pk_fma_f32 v[6:7], v[40:41], v[12:13], v[48:49] op_sel_hi:[1,0,1] neg_lo:[1,0,0] neg_hi:[1,0,0]
	v_pk_fma_f32 v[8:9], v[42:43], v[12:13], v[50:51] op_sel_hi:[1,0,1] neg_lo:[1,0,0] neg_hi:[1,0,0]
	s_waitcnt lgkmcnt(1)
	s_nop 0
	ds_read_b128 v[20:23], v10 offset:41216
	ds_read_b128 v[28:31], v10 offset:41728
	ds_read_b128 v[24:27], v10 offset:41472
	v_fma_mix_f32 v12, v6, v88, v180 op_sel_hi:[0,1,0]
	v_fma_mix_f32 v12, v7, v88, v12 op_sel:[0,1,0] op_sel_hi:[0,1,0]
	v_fma_mix_f32 v12, v8, v89, v12 op_sel_hi:[0,1,0]
	v_fma_mix_f32 v12, v9, v89, v12 op_sel:[0,1,0] op_sel_hi:[0,1,0]
	v_fma_mix_f32 v57, v6, v38, v180 op_sel_hi:[0,1,0]
	v_fma_mix_f32 v57, v7, v38, v57 op_sel:[0,1,0] op_sel_hi:[0,1,0]
	v_add_f32_dpp v12, v12, v12 row_ror:1 row_mask:0xf bank_mask:0xf bound_ctrl:1
	v_fma_mix_f32 v57, v8, v39, v57 op_sel_hi:[0,1,0]
	v_fma_mix_f32 v57, v9, v39, v57 op_sel:[0,1,0] op_sel_hi:[0,1,0]
	v_add_f32_dpp v12, v12, v12 row_ror:2 row_mask:0xf bank_mask:0xf bound_ctrl:1
	v_pk_fma_f32 v[48:49], v[96:97], v[72:73], v[6:7] op_sel_hi:[1,0,1]
	v_pk_fma_f32 v[50:51], v[98:99], v[72:73], v[8:9] op_sel_hi:[1,0,1]
	v_add_f32_dpp v12, v12, v12 row_ror:4 row_mask:0xf bank_mask:0xf bound_ctrl:1
	v_add_f32_dpp v137, v137, v137 row_ror:8 row_mask:0xf bank_mask:0xc
	v_add_f32_dpp v137, v129, v129 row_ror:8 row_mask:0xf bank_mask:0x3
	v_add_f32_dpp v12, v12, v12 row_ror:8 row_mask:0xf bank_mask:0xf bound_ctrl:1
	v_pk_fma_f32 v[6:7], v[92:93], v[12:13], v[48:49] op_sel_hi:[1,0,1] neg_lo:[1,0,0] neg_hi:[1,0,0]
	v_pk_fma_f32 v[8:9], v[94:95], v[12:13], v[50:51] op_sel_hi:[1,0,1] neg_lo:[1,0,0] neg_hi:[1,0,0]
	ds_read_b128 v[36:39], v10 offset:42240
	ds_read_b128 v[44:47], v10 offset:42752
	ds_read_b128 v[40:43], v10 offset:42496
	v_fma_mix_f32 v12, v6, v188, v180 op_sel_hi:[0,1,0]
	v_fma_mix_f32 v12, v7, v188, v12 op_sel:[0,1,0] op_sel_hi:[0,1,0]
	v_fma_mix_f32 v12, v8, v189, v12 op_sel_hi:[0,1,0]
	v_fma_mix_f32 v12, v9, v189, v12 op_sel:[0,1,0] op_sel_hi:[0,1,0]
	v_fma_mix_f32 v81, v6, v90, v180 op_sel_hi:[0,1,0]
	v_fma_mix_f32 v81, v7, v90, v81 op_sel:[0,1,0] op_sel_hi:[0,1,0]
	v_add_f32_dpp v12, v12, v12 row_ror:1 row_mask:0xf bank_mask:0xf bound_ctrl:1
	v_fma_mix_f32 v81, v8, v91, v81 op_sel_hi:[0,1,0]
	v_fma_mix_f32 v81, v9, v91, v81 op_sel:[0,1,0] op_sel_hi:[0,1,0]
	v_add_f32_dpp v12, v12, v12 row_ror:2 row_mask:0xf bank_mask:0xf bound_ctrl:1
	v_pk_fma_f32 v[48:49], v[196:197], v[72:73], v[6:7] op_sel:[0,1,0]
	v_pk_fma_f32 v[50:51], v[198:199], v[72:73], v[8:9] op_sel:[0,1,0]
	v_add_f32_dpp v12, v12, v12 row_ror:4 row_mask:0xf bank_mask:0xf bound_ctrl:1
	v_add_f32_dpp v134, v134, v134 row_ror:4 row_mask:0xf bank_mask:0xa
	v_add_f32_dpp v134, v130, v130 row_ror:12 row_mask:0xf bank_mask:0x5
	v_add_f32_dpp v135, v135, v135 row_ror:4 row_mask:0xf bank_mask:0xa
	v_add_f32_dpp v12, v12, v12 row_ror:8 row_mask:0xf bank_mask:0xf bound_ctrl:1
	v_pk_fma_f32 v[6:7], v[192:193], v[12:13], v[48:49] op_sel_hi:[1,0,1] neg_lo:[1,0,0] neg_hi:[1,0,0]
	v_pk_fma_f32 v[8:9], v[194:195], v[12:13], v[50:51] op_sel_hi:[1,0,1] neg_lo:[1,0,0] neg_hi:[1,0,0]
	v_pk_mul_f32 v[6:7], v[6:7], v[184:185]
	v_pk_mul_f32 v[8:9], v[8:9], v[186:187]
	s_waitcnt lgkmcnt(0)
	s_nop 0
	ds_read_b128 v[88:91], v10 offset:43264
	ds_read_b128 v[96:99], v10 offset:43776
	ds_read_b128 v[92:95], v10 offset:43520
	v_fma_mix_f32 v12, v6, v20, v180 op_sel_hi:[0,1,0]
	v_fma_mix_f32 v12, v7, v20, v12 op_sel:[0,1,0] op_sel_hi:[0,1,0]
	v_fma_mix_f32 v12, v8, v21, v12 op_sel_hi:[0,1,0]
	v_fma_mix_f32 v12, v9, v21, v12 op_sel:[0,1,0] op_sel_hi:[0,1,0]
	v_fma_mix_f32 v82, v6, v190, v180 op_sel_hi:[0,1,0]
	v_fma_mix_f32 v82, v7, v190, v82 op_sel:[0,1,0] op_sel_hi:[0,1,0]
	v_add_f32_dpp v12, v12, v12 row_ror:1 row_mask:0xf bank_mask:0xf bound_ctrl:1
	v_fma_mix_f32 v82, v8, v191, v82 op_sel_hi:[0,1,0]
	v_fma_mix_f32 v82, v9, v191, v82 op_sel:[0,1,0] op_sel_hi:[0,1,0]
	v_add_f32_dpp v12, v12, v12 row_ror:2 row_mask:0xf bank_mask:0xf bound_ctrl:1
	v_pk_fma_f32 v[48:49], v[28:29], v[66:67], v[6:7] op_sel_hi:[1,0,1]
	v_pk_fma_f32 v[50:51], v[30:31], v[66:67], v[8:9] op_sel_hi:[1,0,1]
	v_add_f32_dpp v12, v12, v12 row_ror:4 row_mask:0xf bank_mask:0xf bound_ctrl:1
	v_add_f32_dpp v135, v131, v131 row_ror:12 row_mask:0xf bank_mask:0x5
	v_add_f32_dpp v136, v136, v136 row_ror:4 row_mask:0xf bank_mask:0xa
	v_add_f32_dpp v136, v132, v132 row_ror:12 row_mask:0xf bank_mask:0x5
	v_add_f32_dpp v12, v12, v12 row_ror:8 row_mask:0xf bank_mask:0xf bound_ctrl:1
	v_pk_fma_f32 v[6:7], v[24:25], v[12:13], v[48:49] op_sel_hi:[1,0,1] neg_lo:[1,0,0] neg_hi:[1,0,0]
	v_pk_fma_f32 v[8:9], v[26:27], v[12:13], v[50:51] op_sel_hi:[1,0,1] neg_lo:[1,0,0] neg_hi:[1,0,0]
	ds_read_b128 v[188:191], v10 offset:44288
	ds_read_b128 v[184:187], v10 offset:44032
	ds_read_b128 v[196:199], v10 offset:44800
	ds_read_b128 v[192:195], v10 offset:44544
	ds_read_b128 v[70:73], v11 offset:2816
	v_fma_mix_f32 v12, v6, v36, v180 op_sel_hi:[0,1,0]
	v_fma_mix_f32 v12, v7, v36, v12 op_sel:[0,1,0] op_sel_hi:[0,1,0]
	v_fma_mix_f32 v12, v8, v37, v12 op_sel_hi:[0,1,0]
	v_fma_mix_f32 v12, v9, v37, v12 op_sel:[0,1,0] op_sel_hi:[0,1,0]
	v_fma_mix_f32 v83, v6, v22, v180 op_sel_hi:[0,1,0]
	v_fma_mix_f32 v83, v7, v22, v83 op_sel:[0,1,0] op_sel_hi:[0,1,0]
	v_add_f32_dpp v12, v12, v12 row_ror:1 row_mask:0xf bank_mask:0xf bound_ctrl:1
	v_fma_mix_f32 v83, v8, v23, v83 op_sel_hi:[0,1,0]
	v_fma_mix_f32 v83, v9, v23, v83 op_sel:[0,1,0] op_sel_hi:[0,1,0]
	v_add_f32_dpp v12, v12, v12 row_ror:2 row_mask:0xf bank_mask:0xf bound_ctrl:1
	v_pk_fma_f32 v[48:49], v[44:45], v[66:67], v[6:7] op_sel:[0,1,0]
	v_pk_fma_f32 v[50:51], v[46:47], v[66:67], v[8:9] op_sel:[0,1,0]
	v_add_f32_dpp v12, v12, v12 row_ror:4 row_mask:0xf bank_mask:0xf bound_ctrl:1
	v_add_f32_dpp v137, v137, v137 row_ror:4 row_mask:0xf bank_mask:0xa
	v_add_f32_dpp v137, v133, v133 row_ror:12 row_mask:0xf bank_mask:0x5
	v_add_f32_dpp v12, v12, v12 row_ror:8 row_mask:0xf bank_mask:0xf bound_ctrl:1
	v_pk_fma_f32 v[6:7], v[40:41], v[12:13], v[48:49] op_sel_hi:[1,0,1] neg_lo:[1,0,0] neg_hi:[1,0,0]
	v_pk_fma_f32 v[8:9], v[42:43], v[12:13], v[50:51] op_sel_hi:[1,0,1] neg_lo:[1,0,0] neg_hi:[1,0,0]
	s_waitcnt lgkmcnt(1)
	s_nop 0
	ds_read_b128 v[20:23], v10 offset:45312
	ds_read_b128 v[28:31], v10 offset:45824
	ds_read_b128 v[24:27], v10 offset:45568
	v_fma_mix_f32 v12, v6, v88, v180 op_sel_hi:[0,1,0]
	v_fma_mix_f32 v12, v7, v88, v12 op_sel:[0,1,0] op_sel_hi:[0,1,0]
	v_fma_mix_f32 v12, v8, v89, v12 op_sel_hi:[0,1,0]
	v_fma_mix_f32 v12, v9, v89, v12 op_sel:[0,1,0] op_sel_hi:[0,1,0]
	v_fma_mix_f32 v100, v6, v38, v180 op_sel_hi:[0,1,0]
	v_fma_mix_f32 v100, v7, v38, v100 op_sel:[0,1,0] op_sel_hi:[0,1,0]
	v_add_f32_dpp v12, v12, v12 row_ror:1 row_mask:0xf bank_mask:0xf bound_ctrl:1
	v_fma_mix_f32 v100, v8, v39, v100 op_sel_hi:[0,1,0]
	v_fma_mix_f32 v100, v9, v39, v100 op_sel:[0,1,0] op_sel_hi:[0,1,0]
	v_add_f32_dpp v12, v12, v12 row_ror:2 row_mask:0xf bank_mask:0xf bound_ctrl:1
	v_pk_fma_f32 v[48:49], v[96:97], v[68:69], v[6:7] op_sel_hi:[1,0,1]
	v_pk_fma_f32 v[50:51], v[98:99], v[68:69], v[8:9] op_sel_hi:[1,0,1]
	v_add_f32_dpp v12, v12, v12 row_ror:4 row_mask:0xf bank_mask:0xf bound_ctrl:1
	v_cndmask_b32_e64 v62, v136, v134, s[38:39]
	v_cndmask_b32_e64 v63, v134, v136, s[38:39]
	v_add_f32_dpp v12, v12, v12 row_ror:8 row_mask:0xf bank_mask:0xf bound_ctrl:1
	v_pk_fma_f32 v[6:7], v[92:93], v[12:13], v[48:49] op_sel_hi:[1,0,1] neg_lo:[1,0,0] neg_hi:[1,0,0]
	v_pk_fma_f32 v[8:9], v[94:95], v[12:13], v[50:51] op_sel_hi:[1,0,1] neg_lo:[1,0,0] neg_hi:[1,0,0]
	ds_read_b128 v[36:39], v10 offset:46336
	ds_read_b128 v[44:47], v10 offset:46848
	ds_read_b128 v[40:43], v10 offset:46592
	v_fma_mix_f32 v12, v6, v188, v180 op_sel_hi:[0,1,0]
	v_fma_mix_f32 v12, v7, v188, v12 op_sel:[0,1,0] op_sel_hi:[0,1,0]
	v_fma_mix_f32 v12, v8, v189, v12 op_sel_hi:[0,1,0]
	v_fma_mix_f32 v12, v9, v189, v12 op_sel:[0,1,0] op_sel_hi:[0,1,0]
	v_fma_mix_f32 v101, v6, v90, v180 op_sel_hi:[0,1,0]
	v_fma_mix_f32 v101, v7, v90, v101 op_sel:[0,1,0] op_sel_hi:[0,1,0]
	v_add_f32_dpp v12, v12, v12 row_ror:1 row_mask:0xf bank_mask:0xf bound_ctrl:1
	v_fma_mix_f32 v101, v8, v91, v101 op_sel_hi:[0,1,0]
	v_fma_mix_f32 v101, v9, v91, v101 op_sel:[0,1,0] op_sel_hi:[0,1,0]
	v_add_f32_dpp v12, v12, v12 row_ror:2 row_mask:0xf bank_mask:0xf bound_ctrl:1
	v_pk_fma_f32 v[48:49], v[196:197], v[68:69], v[6:7] op_sel:[0,1,0]
	v_pk_fma_f32 v[50:51], v[198:199], v[68:69], v[8:9] op_sel:[0,1,0]
	v_add_f32_dpp v12, v12, v12 row_ror:4 row_mask:0xf bank_mask:0xf bound_ctrl:1
	v_cndmask_b32_e64 v64, v137, v135, s[38:39]
	v_cndmask_b32_e64 v65, v135, v137, s[38:39]
	v_add_f32_dpp v12, v12, v12 row_ror:8 row_mask:0xf bank_mask:0xf bound_ctrl:1
	v_pk_fma_f32 v[6:7], v[192:193], v[12:13], v[48:49] op_sel_hi:[1,0,1] neg_lo:[1,0,0] neg_hi:[1,0,0]
	v_pk_fma_f32 v[8:9], v[194:195], v[12:13], v[50:51] op_sel_hi:[1,0,1] neg_lo:[1,0,0] neg_hi:[1,0,0]
	v_pk_mul_f32 v[6:7], v[6:7], v[184:185]
	v_pk_mul_f32 v[8:9], v[8:9], v[186:187]
	s_waitcnt lgkmcnt(0)
	s_nop 0
	ds_read_b128 v[88:91], v10 offset:47360
	ds_read_b128 v[96:99], v10 offset:47872
	ds_read_b128 v[92:95], v10 offset:47616
	v_fma_mix_f32 v12, v6, v20, v180 op_sel_hi:[0,1,0]
	v_fma_mix_f32 v12, v7, v20, v12 op_sel:[0,1,0] op_sel_hi:[0,1,0]
	v_fma_mix_f32 v12, v8, v21, v12 op_sel_hi:[0,1,0]
	v_fma_mix_f32 v12, v9, v21, v12 op_sel:[0,1,0] op_sel_hi:[0,1,0]
	v_fma_mix_f32 v102, v6, v190, v180 op_sel_hi:[0,1,0]
	v_fma_mix_f32 v102, v7, v190, v102 op_sel:[0,1,0] op_sel_hi:[0,1,0]
	v_add_f32_dpp v12, v12, v12 row_ror:1 row_mask:0xf bank_mask:0xf bound_ctrl:1
	v_fma_mix_f32 v102, v8, v191, v102 op_sel_hi:[0,1,0]
	v_fma_mix_f32 v102, v9, v191, v102 op_sel:[0,1,0] op_sel_hi:[0,1,0]
	v_add_f32_dpp v12, v12, v12 row_ror:2 row_mask:0xf bank_mask:0xf bound_ctrl:1
	v_pk_fma_f32 v[48:49], v[28:29], v[70:71], v[6:7] op_sel_hi:[1,0,1]
	v_pk_fma_f32 v[50:51], v[30:31], v[70:71], v[8:9] op_sel_hi:[1,0,1]
	v_add_f32_dpp v12, v12, v12 row_ror:4 row_mask:0xf bank_mask:0xf bound_ctrl:1
	v_add_f32_dpp v62, v63, v62 quad_perm:[2,3,0,1] row_mask:0xf bank_mask:0xf bound_ctrl:1
	v_add_f32_dpp v63, v65, v64 quad_perm:[2,3,0,1] row_mask:0xf bank_mask:0xf bound_ctrl:1
	v_add_f32_dpp v12, v12, v12 row_ror:8 row_mask:0xf bank_mask:0xf bound_ctrl:1
	v_pk_fma_f32 v[6:7], v[24:25], v[12:13], v[48:49] op_sel_hi:[1,0,1] neg_lo:[1,0,0] neg_hi:[1,0,0]
	v_pk_fma_f32 v[8:9], v[26:27], v[12:13], v[50:51] op_sel_hi:[1,0,1] neg_lo:[1,0,0] neg_hi:[1,0,0]
	ds_read_b128 v[188:191], v10 offset:48384
	ds_read_b128 v[184:187], v10 offset:48128
	ds_read_b128 v[196:199], v10 offset:48896
	ds_read_b128 v[192:195], v10 offset:48640
	ds_read_b128 v[66:69], v11 offset:3072
	v_fma_mix_f32 v12, v6, v36, v180 op_sel_hi:[0,1,0]
	v_fma_mix_f32 v12, v7, v36, v12 op_sel:[0,1,0] op_sel_hi:[0,1,0]
	v_fma_mix_f32 v12, v8, v37, v12 op_sel_hi:[0,1,0]
	v_fma_mix_f32 v12, v9, v37, v12 op_sel:[0,1,0] op_sel_hi:[0,1,0]
	v_fma_mix_f32 v103, v6, v22, v180 op_sel_hi:[0,1,0]
	v_fma_mix_f32 v103, v7, v22, v103 op_sel:[0,1,0] op_sel_hi:[0,1,0]
	v_add_f32_dpp v12, v12, v12 row_ror:1 row_mask:0xf bank_mask:0xf bound_ctrl:1
	v_fma_mix_f32 v103, v8, v23, v103 op_sel_hi:[0,1,0]
	v_fma_mix_f32 v103, v9, v23, v103 op_sel:[0,1,0] op_sel_hi:[0,1,0]
	v_add_f32_dpp v12, v12, v12 row_ror:2 row_mask:0xf bank_mask:0xf bound_ctrl:1
	v_pk_fma_f32 v[48:49], v[44:45], v[70:71], v[6:7] op_sel:[0,1,0]
	v_pk_fma_f32 v[50:51], v[46:47], v[70:71], v[8:9] op_sel:[0,1,0]
	v_add_f32_dpp v12, v12, v12 row_ror:4 row_mask:0xf bank_mask:0xf bound_ctrl:1
	v_cndmask_b32_e64 v65, v63, v62, s[40:41]
	v_cndmask_b32_e64 v62, v62, v63, s[40:41]
	v_add_f32_dpp v12, v12, v12 row_ror:8 row_mask:0xf bank_mask:0xf bound_ctrl:1
	v_pk_fma_f32 v[6:7], v[40:41], v[12:13], v[48:49] op_sel_hi:[1,0,1] neg_lo:[1,0,0] neg_hi:[1,0,0]
	v_pk_fma_f32 v[8:9], v[42:43], v[12:13], v[50:51] op_sel_hi:[1,0,1] neg_lo:[1,0,0] neg_hi:[1,0,0]
	s_waitcnt lgkmcnt(1)
	s_nop 0
	ds_read_b128 v[20:23], v10 offset:49408
	ds_read_b128 v[28:31], v10 offset:49920
	ds_read_b128 v[24:27], v10 offset:49664
	v_fma_mix_f32 v12, v6, v88, v180 op_sel_hi:[0,1,0]
	v_fma_mix_f32 v12, v7, v88, v12 op_sel:[0,1,0] op_sel_hi:[0,1,0]
	v_fma_mix_f32 v12, v8, v89, v12 op_sel_hi:[0,1,0]
	v_fma_mix_f32 v12, v9, v89, v12 op_sel:[0,1,0] op_sel_hi:[0,1,0]
	v_fma_mix_f32 v104, v6, v38, v180 op_sel_hi:[0,1,0]
	v_fma_mix_f32 v104, v7, v38, v104 op_sel:[0,1,0] op_sel_hi:[0,1,0]
	v_add_f32_dpp v12, v12, v12 row_ror:1 row_mask:0xf bank_mask:0xf bound_ctrl:1
	v_fma_mix_f32 v104, v8, v39, v104 op_sel_hi:[0,1,0]
	v_fma_mix_f32 v104, v9, v39, v104 op_sel:[0,1,0] op_sel_hi:[0,1,0]
	v_add_f32_dpp v12, v12, v12 row_ror:2 row_mask:0xf bank_mask:0xf bound_ctrl:1
	v_pk_fma_f32 v[48:49], v[96:97], v[72:73], v[6:7] op_sel_hi:[1,0,1]
	v_pk_fma_f32 v[50:51], v[98:99], v[72:73], v[8:9] op_sel_hi:[1,0,1]
	v_add_f32_dpp v12, v12, v12 row_ror:4 row_mask:0xf bank_mask:0xf bound_ctrl:1
	v_add_f32_dpp v62, v62, v65 quad_perm:[1,0,3,2] row_mask:0xf bank_mask:0xf bound_ctrl:1
	v_cvt_pk_bf16_f32 v62, v62, v62
	v_add_f32_dpp v12, v12, v12 row_ror:8 row_mask:0xf bank_mask:0xf bound_ctrl:1
	v_pk_fma_f32 v[6:7], v[92:93], v[12:13], v[48:49] op_sel_hi:[1,0,1] neg_lo:[1,0,0] neg_hi:[1,0,0]
	v_pk_fma_f32 v[8:9], v[94:95], v[12:13], v[50:51] op_sel_hi:[1,0,1] neg_lo:[1,0,0] neg_hi:[1,0,0]
	ds_read_b128 v[36:39], v10 offset:50432
	ds_read_b128 v[44:47], v10 offset:50944
	ds_read_b128 v[40:43], v10 offset:50688
	v_fma_mix_f32 v12, v6, v188, v180 op_sel_hi:[0,1,0]
	v_fma_mix_f32 v12, v7, v188, v12 op_sel:[0,1,0] op_sel_hi:[0,1,0]
	v_fma_mix_f32 v12, v8, v189, v12 op_sel_hi:[0,1,0]
	v_fma_mix_f32 v12, v9, v189, v12 op_sel:[0,1,0] op_sel_hi:[0,1,0]
	v_fma_mix_f32 v105, v6, v90, v180 op_sel_hi:[0,1,0]
	v_fma_mix_f32 v105, v7, v90, v105 op_sel:[0,1,0] op_sel_hi:[0,1,0]
	v_add_f32_dpp v12, v12, v12 row_ror:1 row_mask:0xf bank_mask:0xf bound_ctrl:1
	v_fma_mix_f32 v105, v8, v91, v105 op_sel_hi:[0,1,0]
	v_fma_mix_f32 v105, v9, v91, v105 op_sel:[0,1,0] op_sel_hi:[0,1,0]
	v_add_f32_dpp v12, v12, v12 row_ror:2 row_mask:0xf bank_mask:0xf bound_ctrl:1
	v_pk_fma_f32 v[48:49], v[196:197], v[72:73], v[6:7] op_sel:[0,1,0]
	v_pk_fma_f32 v[50:51], v[198:199], v[72:73], v[8:9] op_sel:[0,1,0]
	v_add_f32_dpp v12, v12, v12 row_ror:4 row_mask:0xf bank_mask:0xf bound_ctrl:1
	global_store_short v[2:3], v62, off
	v_lshl_add_u64 v[2:3], v[2:3], 0, s[84:85]
	v_add_f32_dpp v12, v12, v12 row_ror:8 row_mask:0xf bank_mask:0xf bound_ctrl:1
	v_pk_fma_f32 v[6:7], v[192:193], v[12:13], v[48:49] op_sel_hi:[1,0,1] neg_lo:[1,0,0] neg_hi:[1,0,0]
	v_pk_fma_f32 v[8:9], v[194:195], v[12:13], v[50:51] op_sel_hi:[1,0,1] neg_lo:[1,0,0] neg_hi:[1,0,0]
	v_pk_mul_f32 v[6:7], v[6:7], v[184:185]
	v_pk_mul_f32 v[8:9], v[8:9], v[186:187]
	s_waitcnt lgkmcnt(0)
	s_nop 0
	ds_read_b128 v[88:91], v10 offset:51456
	ds_read_b128 v[96:99], v10 offset:51968
	ds_read_b128 v[92:95], v10 offset:51712
	v_fma_mix_f32 v12, v6, v20, v180 op_sel_hi:[0,1,0]
	v_fma_mix_f32 v12, v7, v20, v12 op_sel:[0,1,0] op_sel_hi:[0,1,0]
	v_fma_mix_f32 v12, v8, v21, v12 op_sel_hi:[0,1,0]
	v_fma_mix_f32 v12, v9, v21, v12 op_sel:[0,1,0] op_sel_hi:[0,1,0]
	v_fma_mix_f32 v61, v6, v190, v180 op_sel_hi:[0,1,0]
	v_fma_mix_f32 v61, v7, v190, v61 op_sel:[0,1,0] op_sel_hi:[0,1,0]
	v_add_f32_dpp v12, v12, v12 row_ror:1 row_mask:0xf bank_mask:0xf bound_ctrl:1
	v_fma_mix_f32 v61, v8, v191, v61 op_sel_hi:[0,1,0]
	v_fma_mix_f32 v61, v9, v191, v61 op_sel:[0,1,0] op_sel_hi:[0,1,0]
	v_add_f32_dpp v12, v12, v12 row_ror:2 row_mask:0xf bank_mask:0xf bound_ctrl:1
	v_pk_fma_f32 v[48:49], v[28:29], v[66:67], v[6:7] op_sel_hi:[1,0,1]
	v_pk_fma_f32 v[50:51], v[30:31], v[66:67], v[8:9] op_sel_hi:[1,0,1]
	v_add_f32_dpp v12, v12, v12 row_ror:4 row_mask:0xf bank_mask:0xf bound_ctrl:1
	s_nop 1
	s_nop 0
	v_add_f32_dpp v12, v12, v12 row_ror:8 row_mask:0xf bank_mask:0xf bound_ctrl:1
	v_pk_fma_f32 v[6:7], v[24:25], v[12:13], v[48:49] op_sel_hi:[1,0,1] neg_lo:[1,0,0] neg_hi:[1,0,0]
	v_pk_fma_f32 v[8:9], v[26:27], v[12:13], v[50:51] op_sel_hi:[1,0,1] neg_lo:[1,0,0] neg_hi:[1,0,0]
	ds_read_b128 v[188:191], v10 offset:52480
	ds_read_b128 v[184:187], v10 offset:52224
	ds_read_b128 v[196:199], v10 offset:52992
	ds_read_b128 v[192:195], v10 offset:52736
	ds_read_b128 v[70:73], v11 offset:3328
	v_fma_mix_f32 v12, v6, v36, v180 op_sel_hi:[0,1,0]
	v_fma_mix_f32 v12, v7, v36, v12 op_sel:[0,1,0] op_sel_hi:[0,1,0]
	v_fma_mix_f32 v12, v8, v37, v12 op_sel_hi:[0,1,0]
	v_fma_mix_f32 v12, v9, v37, v12 op_sel:[0,1,0] op_sel_hi:[0,1,0]
	v_fma_mix_f32 v122, v6, v22, v180 op_sel_hi:[0,1,0]
	v_fma_mix_f32 v122, v7, v22, v122 op_sel:[0,1,0] op_sel_hi:[0,1,0]
	v_add_f32_dpp v12, v12, v12 row_ror:1 row_mask:0xf bank_mask:0xf bound_ctrl:1
	v_fma_mix_f32 v122, v8, v23, v122 op_sel_hi:[0,1,0]
	v_fma_mix_f32 v122, v9, v23, v122 op_sel:[0,1,0] op_sel_hi:[0,1,0]
	v_add_f32_dpp v12, v12, v12 row_ror:2 row_mask:0xf bank_mask:0xf bound_ctrl:1
	v_pk_fma_f32 v[48:49], v[44:45], v[66:67], v[6:7] op_sel:[0,1,0]
	v_pk_fma_f32 v[50:51], v[46:47], v[66:67], v[8:9] op_sel:[0,1,0]
	v_add_f32_dpp v12, v12, v12 row_ror:4 row_mask:0xf bank_mask:0xf bound_ctrl:1
	v_add_f32_dpp v83, v83, v83 row_ror:8 row_mask:0xf bank_mask:0xc
	v_add_f32_dpp v83, v52, v52 row_ror:8 row_mask:0xf bank_mask:0x3
	v_add_f32_dpp v100, v100, v100 row_ror:8 row_mask:0xf bank_mask:0xc
	v_add_f32_dpp v12, v12, v12 row_ror:8 row_mask:0xf bank_mask:0xf bound_ctrl:1
	v_pk_fma_f32 v[6:7], v[40:41], v[12:13], v[48:49] op_sel_hi:[1,0,1] neg_lo:[1,0,0] neg_hi:[1,0,0]
	v_pk_fma_f32 v[8:9], v[42:43], v[12:13], v[50:51] op_sel_hi:[1,0,1] neg_lo:[1,0,0] neg_hi:[1,0,0]
	s_waitcnt lgkmcnt(1)
	s_nop 0
	ds_read_b128 v[20:23], v10 offset:53504
	ds_read_b128 v[28:31], v10 offset:54016
	ds_read_b128 v[24:27], v10 offset:53760
	v_fma_mix_f32 v12, v6, v88, v180 op_sel_hi:[0,1,0]
	v_fma_mix_f32 v12, v7, v88, v12 op_sel:[0,1,0] op_sel_hi:[0,1,0]
	v_fma_mix_f32 v12, v8, v89, v12 op_sel_hi:[0,1,0]
	v_fma_mix_f32 v12, v9, v89, v12 op_sel:[0,1,0] op_sel_hi:[0,1,0]
	v_fma_mix_f32 v123, v6, v38, v180 op_sel_hi:[0,1,0]
	v_fma_mix_f32 v123, v7, v38, v123 op_sel:[0,1,0] op_sel_hi:[0,1,0]
	v_add_f32_dpp v12, v12, v12 row_ror:1 row_mask:0xf bank_mask:0xf bound_ctrl:1
	v_fma_mix_f32 v123, v8, v39, v123 op_sel_hi:[0,1,0]
	v_fma_mix_f32 v123, v9, v39, v123 op_sel:[0,1,0] op_sel_hi:[0,1,0]
	v_add_f32_dpp v12, v12, v12 row_ror:2 row_mask:0xf bank_mask:0xf bound_ctrl:1
	v_pk_fma_f32 v[48:49], v[96:97], v[68:69], v[6:7] op_sel_hi:[1,0,1]
	v_pk_fma_f32 v[50:51], v[98:99], v[68:69], v[8:9] op_sel_hi:[1,0,1]
	v_add_f32_dpp v12, v12, v12 row_ror:4 row_mask:0xf bank_mask:0xf bound_ctrl:1
	v_add_f32_dpp v100, v53, v53 row_ror:8 row_mask:0xf bank_mask:0x3
	v_add_f32_dpp v101, v101, v101 row_ror:8 row_mask:0xf bank_mask:0xc
	v_add_f32_dpp v101, v54, v54 row_ror:8 row_mask:0xf bank_mask:0x3
	v_add_f32_dpp v12, v12, v12 row_ror:8 row_mask:0xf bank_mask:0xf bound_ctrl:1
	v_pk_fma_f32 v[6:7], v[92:93], v[12:13], v[48:49] op_sel_hi:[1,0,1] neg_lo:[1,0,0] neg_hi:[1,0,0]
	v_pk_fma_f32 v[8:9], v[94:95], v[12:13], v[50:51] op_sel_hi:[1,0,1] neg_lo:[1,0,0] neg_hi:[1,0,0]
	ds_read_b128 v[36:39], v10 offset:54528
	ds_read_b128 v[44:47], v10 offset:55040
	ds_read_b128 v[40:43], v10 offset:54784
	v_fma_mix_f32 v12, v6, v188, v180 op_sel_hi:[0,1,0]
	v_fma_mix_f32 v12, v7, v188, v12 op_sel:[0,1,0] op_sel_hi:[0,1,0]
	v_fma_mix_f32 v12, v8, v189, v12 op_sel_hi:[0,1,0]
	v_fma_mix_f32 v12, v9, v189, v12 op_sel:[0,1,0] op_sel_hi:[0,1,0]
	v_fma_mix_f32 v124, v6, v90, v180 op_sel_hi:[0,1,0]
	v_fma_mix_f32 v124, v7, v90, v124 op_sel:[0,1,0] op_sel_hi:[0,1,0]
	v_add_f32_dpp v12, v12, v12 row_ror:1 row_mask:0xf bank_mask:0xf bound_ctrl:1
	v_fma_mix_f32 v124, v8, v91, v124 op_sel_hi:[0,1,0]
	v_fma_mix_f32 v124, v9, v91, v124 op_sel:[0,1,0] op_sel_hi:[0,1,0]
	v_add_f32_dpp v12, v12, v12 row_ror:2 row_mask:0xf bank_mask:0xf bound_ctrl:1
	v_pk_fma_f32 v[48:49], v[196:197], v[68:69], v[6:7] op_sel:[0,1,0]
	v_pk_fma_f32 v[50:51], v[198:199], v[68:69], v[8:9] op_sel:[0,1,0]
	v_add_f32_dpp v12, v12, v12 row_ror:4 row_mask:0xf bank_mask:0xf bound_ctrl:1
	v_add_f32_dpp v102, v102, v102 row_ror:8 row_mask:0xf bank_mask:0xc
	v_add_f32_dpp v102, v55, v55 row_ror:8 row_mask:0xf bank_mask:0x3
	v_add_f32_dpp v103, v103, v103 row_ror:8 row_mask:0xf bank_mask:0xc
	v_add_f32_dpp v12, v12, v12 row_ror:8 row_mask:0xf bank_mask:0xf bound_ctrl:1
	v_pk_fma_f32 v[6:7], v[192:193], v[12:13], v[48:49] op_sel_hi:[1,0,1] neg_lo:[1,0,0] neg_hi:[1,0,0]
	v_pk_fma_f32 v[8:9], v[194:195], v[12:13], v[50:51] op_sel_hi:[1,0,1] neg_lo:[1,0,0] neg_hi:[1,0,0]
	v_pk_mul_f32 v[6:7], v[6:7], v[184:185]
	v_pk_mul_f32 v[8:9], v[8:9], v[186:187]
	s_waitcnt lgkmcnt(0)
	s_nop 0
	ds_read_b128 v[88:91], v10 offset:55552
	ds_read_b128 v[96:99], v10 offset:56064
	ds_read_b128 v[92:95], v10 offset:55808
	v_fma_mix_f32 v12, v6, v20, v180 op_sel_hi:[0,1,0]
	v_fma_mix_f32 v12, v7, v20, v12 op_sel:[0,1,0] op_sel_hi:[0,1,0]
	v_fma_mix_f32 v12, v8, v21, v12 op_sel_hi:[0,1,0]
	v_fma_mix_f32 v12, v9, v21, v12 op_sel:[0,1,0] op_sel_hi:[0,1,0]
	v_fma_mix_f32 v125, v6, v190, v180 op_sel_hi:[0,1,0]
	v_fma_mix_f32 v125, v7, v190, v125 op_sel:[0,1,0] op_sel_hi:[0,1,0]
	v_add_f32_dpp v12, v12, v12 row_ror:1 row_mask:0xf bank_mask:0xf bound_ctrl:1
	v_fma_mix_f32 v125, v8, v191, v125 op_sel_hi:[0,1,0]
	v_fma_mix_f32 v125, v9, v191, v125 op_sel:[0,1,0] op_sel_hi:[0,1,0]
	v_add_f32_dpp v12, v12, v12 row_ror:2 row_mask:0xf bank_mask:0xf bound_ctrl:1
	v_pk_fma_f32 v[48:49], v[28:29], v[70:71], v[6:7] op_sel_hi:[1,0,1]
	v_pk_fma_f32 v[50:51], v[30:31], v[70:71], v[8:9] op_sel_hi:[1,0,1]
	v_add_f32_dpp v12, v12, v12 row_ror:4 row_mask:0xf bank_mask:0xf bound_ctrl:1
	v_add_f32_dpp v103, v56, v56 row_ror:8 row_mask:0xf bank_mask:0x3
	v_add_f32_dpp v104, v104, v104 row_ror:8 row_mask:0xf bank_mask:0xc
	v_add_f32_dpp v104, v57, v57 row_ror:8 row_mask:0xf bank_mask:0x3
	v_add_f32_dpp v12, v12, v12 row_ror:8 row_mask:0xf bank_mask:0xf bound_ctrl:1
	v_pk_fma_f32 v[6:7], v[24:25], v[12:13], v[48:49] op_sel_hi:[1,0,1] neg_lo:[1,0,0] neg_hi:[1,0,0]
	v_pk_fma_f32 v[8:9], v[26:27], v[12:13], v[50:51] op_sel_hi:[1,0,1] neg_lo:[1,0,0] neg_hi:[1,0,0]
	ds_read_b128 v[188:191], v10 offset:56576
	ds_read_b128 v[184:187], v10 offset:56320
	ds_read_b128 v[196:199], v10 offset:57088
	ds_read_b128 v[192:195], v10 offset:56832
	ds_read_b128 v[66:69], v11 offset:3584
	v_fma_mix_f32 v12, v6, v36, v180 op_sel_hi:[0,1,0]
	v_fma_mix_f32 v12, v7, v36, v12 op_sel:[0,1,0] op_sel_hi:[0,1,0]
	v_fma_mix_f32 v12, v8, v37, v12 op_sel_hi:[0,1,0]
	v_fma_mix_f32 v12, v9, v37, v12 op_sel:[0,1,0] op_sel_hi:[0,1,0]
	v_fma_mix_f32 v126, v6, v22, v180 op_sel_hi:[0,1,0]
	v_fma_mix_f32 v126, v7, v22, v126 op_sel:[0,1,0] op_sel_hi:[0,1,0]
	v_add_f32_dpp v12, v12, v12 row_ror:1 row_mask:0xf bank_mask:0xf bound_ctrl:1
	v_fma_mix_f32 v126, v8, v23, v126 op_sel_hi:[0,1,0]
	v_fma_mix_f32 v126, v9, v23, v126 op_sel:[0,1,0] op_sel_hi:[0,1,0]
	v_add_f32_dpp v12, v12, v12 row_ror:2 row_mask:0xf bank_mask:0xf bound_ctrl:1
	v_pk_fma_f32 v[48:49], v[44:45], v[70:71], v[6:7] op_sel:[0,1,0]
	v_pk_fma_f32 v[50:51], v[46:47], v[70:71], v[8:9] op_sel:[0,1,0]
	v_add_f32_dpp v12, v12, v12 row_ror:4 row_mask:0xf bank_mask:0xf bound_ctrl:1
	v_add_f32_dpp v105, v105, v105 row_ror:8 row_mask:0xf bank_mask:0xc
	v_add_f32_dpp v105, v81, v81 row_ror:8 row_mask:0xf bank_mask:0x3
	v_add_f32_dpp v12, v12, v12 row_ror:8 row_mask:0xf bank_mask:0xf bound_ctrl:1
	v_pk_fma_f32 v[6:7], v[40:41], v[12:13], v[48:49] op_sel_hi:[1,0,1] neg_lo:[1,0,0] neg_hi:[1,0,0]
	v_pk_fma_f32 v[8:9], v[42:43], v[12:13], v[50:51] op_sel_hi:[1,0,1] neg_lo:[1,0,0] neg_hi:[1,0,0]
	s_waitcnt lgkmcnt(1)
	s_nop 0
	ds_read_b128 v[20:23], v10 offset:57600
	ds_read_b128 v[28:31], v10 offset:58112
	ds_read_b128 v[24:27], v10 offset:57856
	v_fma_mix_f32 v12, v6, v88, v180 op_sel_hi:[0,1,0]
	v_fma_mix_f32 v12, v7, v88, v12 op_sel:[0,1,0] op_sel_hi:[0,1,0]
	v_fma_mix_f32 v12, v8, v89, v12 op_sel_hi:[0,1,0]
	v_fma_mix_f32 v12, v9, v89, v12 op_sel:[0,1,0] op_sel_hi:[0,1,0]
	v_fma_mix_f32 v127, v6, v38, v180 op_sel_hi:[0,1,0]
	v_fma_mix_f32 v127, v7, v38, v127 op_sel:[0,1,0] op_sel_hi:[0,1,0]
	v_add_f32_dpp v12, v12, v12 row_ror:1 row_mask:0xf bank_mask:0xf bound_ctrl:1
	v_fma_mix_f32 v127, v8, v39, v127 op_sel_hi:[0,1,0]
	v_fma_mix_f32 v127, v9, v39, v127 op_sel:[0,1,0] op_sel_hi:[0,1,0]
	v_add_f32_dpp v12, v12, v12 row_ror:2 row_mask:0xf bank_mask:0xf bound_ctrl:1
	v_pk_fma_f32 v[48:49], v[96:97], v[72:73], v[6:7] op_sel_hi:[1,0,1]
	v_pk_fma_f32 v[50:51], v[98:99], v[72:73], v[8:9] op_sel_hi:[1,0,1]
	v_add_f32_dpp v12, v12, v12 row_ror:4 row_mask:0xf bank_mask:0xf bound_ctrl:1
	v_add_f32_dpp v61, v61, v61 row_ror:8 row_mask:0xf bank_mask:0xc
	v_add_f32_dpp v61, v82, v82 row_ror:8 row_mask:0xf bank_mask:0x3
	v_add_f32_dpp v12, v12, v12 row_ror:8 row_mask:0xf bank_mask:0xf bound_ctrl:1
	v_pk_fma_f32 v[6:7], v[92:93], v[12:13], v[48:49] op_sel_hi:[1,0,1] neg_lo:[1,0,0] neg_hi:[1,0,0]
	v_pk_fma_f32 v[8:9], v[94:95], v[12:13], v[50:51] op_sel_hi:[1,0,1] neg_lo:[1,0,0] neg_hi:[1,0,0]
	ds_read_b128 v[36:39], v10 offset:58624
	ds_read_b128 v[44:47], v10 offset:59136
	ds_read_b128 v[40:43], v10 offset:58880
	v_fma_mix_f32 v12, v6, v188, v180 op_sel_hi:[0,1,0]
	v_fma_mix_f32 v12, v7, v188, v12 op_sel:[0,1,0] op_sel_hi:[0,1,0]
	v_fma_mix_f32 v12, v8, v189, v12 op_sel_hi:[0,1,0]
	v_fma_mix_f32 v12, v9, v189, v12 op_sel:[0,1,0] op_sel_hi:[0,1,0]
	v_fma_mix_f32 v128, v6, v90, v180 op_sel_hi:[0,1,0]
	v_fma_mix_f32 v128, v7, v90, v128 op_sel:[0,1,0] op_sel_hi:[0,1,0]
	v_add_f32_dpp v12, v12, v12 row_ror:1 row_mask:0xf bank_mask:0xf bound_ctrl:1
	v_fma_mix_f32 v128, v8, v91, v128 op_sel_hi:[0,1,0]
	v_fma_mix_f32 v128, v9, v91, v128 op_sel:[0,1,0] op_sel_hi:[0,1,0]
	v_add_f32_dpp v12, v12, v12 row_ror:2 row_mask:0xf bank_mask:0xf bound_ctrl:1
	v_pk_fma_f32 v[48:49], v[196:197], v[72:73], v[6:7] op_sel:[0,1,0]
	v_pk_fma_f32 v[50:51], v[198:199], v[72:73], v[8:9] op_sel:[0,1,0]
	v_add_f32_dpp v12, v12, v12 row_ror:4 row_mask:0xf bank_mask:0xf bound_ctrl:1
	v_add_f32_dpp v103, v103, v103 row_ror:4 row_mask:0xf bank_mask:0xa
	v_add_f32_dpp v103, v83, v83 row_ror:12 row_mask:0xf bank_mask:0x5
	v_add_f32_dpp v104, v104, v104 row_ror:4 row_mask:0xf bank_mask:0xa
	v_add_f32_dpp v12, v12, v12 row_ror:8 row_mask:0xf bank_mask:0xf bound_ctrl:1
	v_pk_fma_f32 v[6:7], v[192:193], v[12:13], v[48:49] op_sel_hi:[1,0,1] neg_lo:[1,0,0] neg_hi:[1,0,0]
	v_pk_fma_f32 v[8:9], v[194:195], v[12:13], v[50:51] op_sel_hi:[1,0,1] neg_lo:[1,0,0] neg_hi:[1,0,0]
	v_pk_mul_f32 v[6:7], v[6:7], v[184:185]
	v_pk_mul_f32 v[8:9], v[8:9], v[186:187]
	s_waitcnt lgkmcnt(0)
	s_nop 0
	ds_read_b128 v[88:91], v10 offset:59648
	ds_read_b128 v[96:99], v10 offset:60160
	ds_read_b128 v[92:95], v10 offset:59904
	v_fma_mix_f32 v12, v6, v20, v180 op_sel_hi:[0,1,0]
	v_fma_mix_f32 v12, v7, v20, v12 op_sel:[0,1,0] op_sel_hi:[0,1,0]
	v_fma_mix_f32 v12, v8, v21, v12 op_sel_hi:[0,1,0]
	v_fma_mix_f32 v12, v9, v21, v12 op_sel:[0,1,0] op_sel_hi:[0,1,0]
	v_fma_mix_f32 v129, v6, v190, v180 op_sel_hi:[0,1,0]
	v_fma_mix_f32 v129, v7, v190, v129 op_sel:[0,1,0] op_sel_hi:[0,1,0]
	v_add_f32_dpp v12, v12, v12 row_ror:1 row_mask:0xf bank_mask:0xf bound_ctrl:1
	v_fma_mix_f32 v129, v8, v191, v129 op_sel_hi:[0,1,0]
	v_fma_mix_f32 v129, v9, v191, v129 op_sel:[0,1,0] op_sel_hi:[0,1,0]
	v_add_f32_dpp v12, v12, v12 row_ror:2 row_mask:0xf bank_mask:0xf bound_ctrl:1
	v_pk_fma_f32 v[48:49], v[28:29], v[66:67], v[6:7] op_sel_hi:[1,0,1]
	v_pk_fma_f32 v[50:51], v[30:31], v[66:67], v[8:9] op_sel_hi:[1,0,1]
	v_add_f32_dpp v12, v12, v12 row_ror:4 row_mask:0xf bank_mask:0xf bound_ctrl:1
	v_add_f32_dpp v104, v100, v100 row_ror:12 row_mask:0xf bank_mask:0x5
	v_add_f32_dpp v105, v105, v105 row_ror:4 row_mask:0xf bank_mask:0xa
	v_add_f32_dpp v105, v101, v101 row_ror:12 row_mask:0xf bank_mask:0x5
	v_add_f32_dpp v12, v12, v12 row_ror:8 row_mask:0xf bank_mask:0xf bound_ctrl:1
	v_pk_fma_f32 v[6:7], v[24:25], v[12:13], v[48:49] op_sel_hi:[1,0,1] neg_lo:[1,0,0] neg_hi:[1,0,0]
	v_pk_fma_f32 v[8:9], v[26:27], v[12:13], v[50:51] op_sel_hi:[1,0,1] neg_lo:[1,0,0] neg_hi:[1,0,0]
	ds_read_b128 v[188:191], v10 offset:60672
	ds_read_b128 v[184:187], v10 offset:60416
	ds_read_b128 v[196:199], v10 offset:61184
	ds_read_b128 v[192:195], v10 offset:60928
	ds_read_b128 v[70:73], v11 offset:3840
	v_fma_mix_f32 v12, v6, v36, v180 op_sel_hi:[0,1,0]
	v_fma_mix_f32 v12, v7, v36, v12 op_sel:[0,1,0] op_sel_hi:[0,1,0]
	v_fma_mix_f32 v12, v8, v37, v12 op_sel_hi:[0,1,0]
	v_fma_mix_f32 v12, v9, v37, v12 op_sel:[0,1,0] op_sel_hi:[0,1,0]
	v_fma_mix_f32 v130, v6, v22, v180 op_sel_hi:[0,1,0]
	v_fma_mix_f32 v130, v7, v22, v130 op_sel:[0,1,0] op_sel_hi:[0,1,0]
	v_add_f32_dpp v12, v12, v12 row_ror:1 row_mask:0xf bank_mask:0xf bound_ctrl:1
	v_fma_mix_f32 v130, v8, v23, v130 op_sel_hi:[0,1,0]
	v_fma_mix_f32 v130, v9, v23, v130 op_sel:[0,1,0] op_sel_hi:[0,1,0]
	v_add_f32_dpp v12, v12, v12 row_ror:2 row_mask:0xf bank_mask:0xf bound_ctrl:1
	v_pk_fma_f32 v[48:49], v[44:45], v[66:67], v[6:7] op_sel:[0,1,0]
	v_pk_fma_f32 v[50:51], v[46:47], v[66:67], v[8:9] op_sel:[0,1,0]
	v_add_f32_dpp v12, v12, v12 row_ror:4 row_mask:0xf bank_mask:0xf bound_ctrl:1
	v_add_f32_dpp v61, v61, v61 row_ror:4 row_mask:0xf bank_mask:0xa
	v_add_f32_dpp v61, v102, v102 row_ror:12 row_mask:0xf bank_mask:0x5
	v_add_f32_dpp v12, v12, v12 row_ror:8 row_mask:0xf bank_mask:0xf bound_ctrl:1
	v_pk_fma_f32 v[6:7], v[40:41], v[12:13], v[48:49] op_sel_hi:[1,0,1] neg_lo:[1,0,0] neg_hi:[1,0,0]
	v_pk_fma_f32 v[8:9], v[42:43], v[12:13], v[50:51] op_sel_hi:[1,0,1] neg_lo:[1,0,0] neg_hi:[1,0,0]
	s_waitcnt lgkmcnt(1)
	s_nop 0
	ds_read_b128 v[20:23], v10 offset:61696
	ds_read_b128 v[28:31], v10 offset:62208
	ds_read_b128 v[24:27], v10 offset:61952
	v_fma_mix_f32 v12, v6, v88, v180 op_sel_hi:[0,1,0]
	v_fma_mix_f32 v12, v7, v88, v12 op_sel:[0,1,0] op_sel_hi:[0,1,0]
	v_fma_mix_f32 v12, v8, v89, v12 op_sel_hi:[0,1,0]
	v_fma_mix_f32 v12, v9, v89, v12 op_sel:[0,1,0] op_sel_hi:[0,1,0]
	v_fma_mix_f32 v131, v6, v38, v180 op_sel_hi:[0,1,0]
	v_fma_mix_f32 v131, v7, v38, v131 op_sel:[0,1,0] op_sel_hi:[0,1,0]
	v_add_f32_dpp v12, v12, v12 row_ror:1 row_mask:0xf bank_mask:0xf bound_ctrl:1
	v_fma_mix_f32 v131, v8, v39, v131 op_sel_hi:[0,1,0]
	v_fma_mix_f32 v131, v9, v39, v131 op_sel:[0,1,0] op_sel_hi:[0,1,0]
	v_add_f32_dpp v12, v12, v12 row_ror:2 row_mask:0xf bank_mask:0xf bound_ctrl:1
	v_pk_fma_f32 v[48:49], v[96:97], v[68:69], v[6:7] op_sel_hi:[1,0,1]
	v_pk_fma_f32 v[50:51], v[98:99], v[68:69], v[8:9] op_sel_hi:[1,0,1]
	v_add_f32_dpp v12, v12, v12 row_ror:4 row_mask:0xf bank_mask:0xf bound_ctrl:1
	v_cndmask_b32_e64 v62, v105, v103, s[38:39]
	v_cndmask_b32_e64 v63, v103, v105, s[38:39]
	v_add_f32_dpp v12, v12, v12 row_ror:8 row_mask:0xf bank_mask:0xf bound_ctrl:1
	v_pk_fma_f32 v[6:7], v[92:93], v[12:13], v[48:49] op_sel_hi:[1,0,1] neg_lo:[1,0,0] neg_hi:[1,0,0]
	v_pk_fma_f32 v[8:9], v[94:95], v[12:13], v[50:51] op_sel_hi:[1,0,1] neg_lo:[1,0,0] neg_hi:[1,0,0]
	ds_read_b128 v[36:39], v10 offset:62720
	ds_read_b128 v[44:47], v10 offset:63232
	ds_read_b128 v[40:43], v10 offset:62976
	v_fma_mix_f32 v12, v6, v188, v180 op_sel_hi:[0,1,0]
	v_fma_mix_f32 v12, v7, v188, v12 op_sel:[0,1,0] op_sel_hi:[0,1,0]
	v_fma_mix_f32 v12, v8, v189, v12 op_sel_hi:[0,1,0]
	v_fma_mix_f32 v12, v9, v189, v12 op_sel:[0,1,0] op_sel_hi:[0,1,0]
	v_fma_mix_f32 v132, v6, v90, v180 op_sel_hi:[0,1,0]
	v_fma_mix_f32 v132, v7, v90, v132 op_sel:[0,1,0] op_sel_hi:[0,1,0]
	v_add_f32_dpp v12, v12, v12 row_ror:1 row_mask:0xf bank_mask:0xf bound_ctrl:1
	v_fma_mix_f32 v132, v8, v91, v132 op_sel_hi:[0,1,0]
	v_fma_mix_f32 v132, v9, v91, v132 op_sel:[0,1,0] op_sel_hi:[0,1,0]
	v_add_f32_dpp v12, v12, v12 row_ror:2 row_mask:0xf bank_mask:0xf bound_ctrl:1
	v_pk_fma_f32 v[48:49], v[196:197], v[68:69], v[6:7] op_sel:[0,1,0]
	v_pk_fma_f32 v[50:51], v[198:199], v[68:69], v[8:9] op_sel:[0,1,0]
	v_add_f32_dpp v12, v12, v12 row_ror:4 row_mask:0xf bank_mask:0xf bound_ctrl:1
	v_cndmask_b32_e64 v64, v61, v104, s[38:39]
	v_cndmask_b32_e64 v65, v104, v61, s[38:39]
	v_add_f32_dpp v12, v12, v12 row_ror:8 row_mask:0xf bank_mask:0xf bound_ctrl:1
	v_pk_fma_f32 v[6:7], v[192:193], v[12:13], v[48:49] op_sel_hi:[1,0,1] neg_lo:[1,0,0] neg_hi:[1,0,0]
	v_pk_fma_f32 v[8:9], v[194:195], v[12:13], v[50:51] op_sel_hi:[1,0,1] neg_lo:[1,0,0] neg_hi:[1,0,0]
	v_pk_mul_f32 v[6:7], v[6:7], v[184:185]
	v_pk_mul_f32 v[8:9], v[8:9], v[186:187]
	s_waitcnt lgkmcnt(0)
	s_nop 0
	ds_read_b128 v[88:91], v10 offset:63744
	ds_read_b128 v[96:99], v10 offset:64256
	ds_read_b128 v[92:95], v10 offset:64000
	v_fma_mix_f32 v12, v6, v20, v180 op_sel_hi:[0,1,0]
	v_fma_mix_f32 v12, v7, v20, v12 op_sel:[0,1,0] op_sel_hi:[0,1,0]
	v_fma_mix_f32 v12, v8, v21, v12 op_sel_hi:[0,1,0]
	v_fma_mix_f32 v12, v9, v21, v12 op_sel:[0,1,0] op_sel_hi:[0,1,0]
	v_fma_mix_f32 v133, v6, v190, v180 op_sel_hi:[0,1,0]
	v_fma_mix_f32 v133, v7, v190, v133 op_sel:[0,1,0] op_sel_hi:[0,1,0]
	v_add_f32_dpp v12, v12, v12 row_ror:1 row_mask:0xf bank_mask:0xf bound_ctrl:1
	v_fma_mix_f32 v133, v8, v191, v133 op_sel_hi:[0,1,0]
	v_fma_mix_f32 v133, v9, v191, v133 op_sel:[0,1,0] op_sel_hi:[0,1,0]
	v_add_f32_dpp v12, v12, v12 row_ror:2 row_mask:0xf bank_mask:0xf bound_ctrl:1
	v_pk_fma_f32 v[48:49], v[28:29], v[70:71], v[6:7] op_sel_hi:[1,0,1]
	v_pk_fma_f32 v[50:51], v[30:31], v[70:71], v[8:9] op_sel_hi:[1,0,1]
	v_add_f32_dpp v12, v12, v12 row_ror:4 row_mask:0xf bank_mask:0xf bound_ctrl:1
	v_add_f32_dpp v62, v63, v62 quad_perm:[2,3,0,1] row_mask:0xf bank_mask:0xf bound_ctrl:1
	v_add_f32_dpp v63, v65, v64 quad_perm:[2,3,0,1] row_mask:0xf bank_mask:0xf bound_ctrl:1
	v_add_f32_dpp v12, v12, v12 row_ror:8 row_mask:0xf bank_mask:0xf bound_ctrl:1
	v_pk_fma_f32 v[6:7], v[24:25], v[12:13], v[48:49] op_sel_hi:[1,0,1] neg_lo:[1,0,0] neg_hi:[1,0,0]
	v_pk_fma_f32 v[8:9], v[26:27], v[12:13], v[50:51] op_sel_hi:[1,0,1] neg_lo:[1,0,0] neg_hi:[1,0,0]
	ds_read_b128 v[188:191], v10 offset:64768
	ds_read_b128 v[184:187], v10 offset:64512
	ds_read_b128 v[196:199], v10 offset:65280
	ds_read_b128 v[192:195], v10 offset:65024
	v_fma_mix_f32 v12, v6, v36, v180 op_sel_hi:[0,1,0]
	v_fma_mix_f32 v12, v7, v36, v12 op_sel:[0,1,0] op_sel_hi:[0,1,0]
	v_fma_mix_f32 v12, v8, v37, v12 op_sel_hi:[0,1,0]
	v_fma_mix_f32 v12, v9, v37, v12 op_sel:[0,1,0] op_sel_hi:[0,1,0]
	v_fma_mix_f32 v134, v6, v22, v180 op_sel_hi:[0,1,0]
	v_fma_mix_f32 v134, v7, v22, v134 op_sel:[0,1,0] op_sel_hi:[0,1,0]
	v_add_f32_dpp v12, v12, v12 row_ror:1 row_mask:0xf bank_mask:0xf bound_ctrl:1
	v_fma_mix_f32 v134, v8, v23, v134 op_sel_hi:[0,1,0]
	v_fma_mix_f32 v134, v9, v23, v134 op_sel:[0,1,0] op_sel_hi:[0,1,0]
	v_add_f32_dpp v12, v12, v12 row_ror:2 row_mask:0xf bank_mask:0xf bound_ctrl:1
	v_pk_fma_f32 v[48:49], v[44:45], v[70:71], v[6:7] op_sel:[0,1,0]
	v_pk_fma_f32 v[50:51], v[46:47], v[70:71], v[8:9] op_sel:[0,1,0]
	v_add_f32_dpp v12, v12, v12 row_ror:4 row_mask:0xf bank_mask:0xf bound_ctrl:1
	v_cndmask_b32_e64 v65, v63, v62, s[40:41]
	v_cndmask_b32_e64 v62, v62, v63, s[40:41]
	v_add_f32_dpp v12, v12, v12 row_ror:8 row_mask:0xf bank_mask:0xf bound_ctrl:1
	v_pk_fma_f32 v[6:7], v[40:41], v[12:13], v[48:49] op_sel_hi:[1,0,1] neg_lo:[1,0,0] neg_hi:[1,0,0]
	v_pk_fma_f32 v[8:9], v[42:43], v[12:13], v[50:51] op_sel_hi:[1,0,1] neg_lo:[1,0,0] neg_hi:[1,0,0]
	s_waitcnt lgkmcnt(0)
	s_nop 0
	v_fma_mix_f32 v12, v6, v88, v180 op_sel_hi:[0,1,0]
	v_fma_mix_f32 v12, v7, v88, v12 op_sel:[0,1,0] op_sel_hi:[0,1,0]
	v_fma_mix_f32 v12, v8, v89, v12 op_sel_hi:[0,1,0]
	v_fma_mix_f32 v12, v9, v89, v12 op_sel:[0,1,0] op_sel_hi:[0,1,0]
	v_fma_mix_f32 v135, v6, v38, v180 op_sel_hi:[0,1,0]
	v_fma_mix_f32 v135, v7, v38, v135 op_sel:[0,1,0] op_sel_hi:[0,1,0]
	v_add_f32_dpp v12, v12, v12 row_ror:1 row_mask:0xf bank_mask:0xf bound_ctrl:1
	v_fma_mix_f32 v135, v8, v39, v135 op_sel_hi:[0,1,0]
	v_fma_mix_f32 v135, v9, v39, v135 op_sel:[0,1,0] op_sel_hi:[0,1,0]
	v_add_f32_dpp v12, v12, v12 row_ror:2 row_mask:0xf bank_mask:0xf bound_ctrl:1
	v_pk_fma_f32 v[48:49], v[96:97], v[72:73], v[6:7] op_sel_hi:[1,0,1]
	v_pk_fma_f32 v[50:51], v[98:99], v[72:73], v[8:9] op_sel_hi:[1,0,1]
	v_add_f32_dpp v12, v12, v12 row_ror:4 row_mask:0xf bank_mask:0xf bound_ctrl:1
	v_add_f32_dpp v62, v62, v65 quad_perm:[1,0,3,2] row_mask:0xf bank_mask:0xf bound_ctrl:1
	v_cvt_pk_bf16_f32 v62, v62, v62
	v_add_f32_dpp v12, v12, v12 row_ror:8 row_mask:0xf bank_mask:0xf bound_ctrl:1
	v_pk_fma_f32 v[6:7], v[92:93], v[12:13], v[48:49] op_sel_hi:[1,0,1] neg_lo:[1,0,0] neg_hi:[1,0,0]
	v_pk_fma_f32 v[8:9], v[94:95], v[12:13], v[50:51] op_sel_hi:[1,0,1] neg_lo:[1,0,0] neg_hi:[1,0,0]
	s_waitcnt lgkmcnt(0)
	s_barrier
	v_xor_b32_e32 v10, 0x10000, v10
	v_xor_b32_e32 v11, 0x1000, v11
	ds_read_b128 v[66:69], v11 offset:0
	ds_read_b128 v[20:23], v10 offset:256
	ds_read_b128 v[28:31], v10 offset:768
	ds_read_b128 v[24:27], v10 offset:512
	ds_read_b128 v[36:39], v10 offset:1280
	ds_read_b128 v[44:47], v10 offset:1792
	ds_read_b128 v[40:43], v10 offset:1536
	v_fma_mix_f32 v12, v6, v188, v180 op_sel_hi:[0,1,0]
	v_fma_mix_f32 v12, v7, v188, v12 op_sel:[0,1,0] op_sel_hi:[0,1,0]
	v_fma_mix_f32 v12, v8, v189, v12 op_sel_hi:[0,1,0]
	v_fma_mix_f32 v12, v9, v189, v12 op_sel:[0,1,0] op_sel_hi:[0,1,0]
	v_fma_mix_f32 v136, v6, v90, v180 op_sel_hi:[0,1,0]
	v_fma_mix_f32 v136, v7, v90, v136 op_sel:[0,1,0] op_sel_hi:[0,1,0]
	v_add_f32_dpp v12, v12, v12 row_ror:1 row_mask:0xf bank_mask:0xf bound_ctrl:1
	v_fma_mix_f32 v136, v8, v91, v136 op_sel_hi:[0,1,0]
	v_fma_mix_f32 v136, v9, v91, v136 op_sel:[0,1,0] op_sel_hi:[0,1,0]
	v_add_f32_dpp v12, v12, v12 row_ror:2 row_mask:0xf bank_mask:0xf bound_ctrl:1
	v_pk_fma_f32 v[48:49], v[196:197], v[72:73], v[6:7] op_sel:[0,1,0]
	v_pk_fma_f32 v[50:51], v[198:199], v[72:73], v[8:9] op_sel:[0,1,0]
	v_add_f32_dpp v12, v12, v12 row_ror:4 row_mask:0xf bank_mask:0xf bound_ctrl:1
	global_store_short v[2:3], v62, off
	v_lshl_add_u64 v[2:3], v[2:3], 0, s[84:85]
	v_add_f32_dpp v12, v12, v12 row_ror:8 row_mask:0xf bank_mask:0xf bound_ctrl:1
	v_pk_fma_f32 v[6:7], v[192:193], v[12:13], v[48:49] op_sel_hi:[1,0,1] neg_lo:[1,0,0] neg_hi:[1,0,0]
	v_pk_fma_f32 v[8:9], v[194:195], v[12:13], v[50:51] op_sel_hi:[1,0,1] neg_lo:[1,0,0] neg_hi:[1,0,0]
	v_pk_mul_f32 v[6:7], v[6:7], v[184:185]
	v_pk_mul_f32 v[8:9], v[8:9], v[186:187]
	v_fma_mix_f32 v137, v6, v190, v180 op_sel_hi:[0,1,0]
	v_fma_mix_f32 v137, v7, v190, v137 op_sel:[0,1,0] op_sel_hi:[0,1,0]
	v_fma_mix_f32 v137, v8, v191, v137 op_sel_hi:[0,1,0]
	v_fma_mix_f32 v137, v9, v191, v137 op_sel:[0,1,0] op_sel_hi:[0,1,0]
	v_mov_b32_e64 v170, v2
	v_mov_b32_e64 v171, v3
	s_mov_b64 s[100:101], -1
	s_nop 0
	s_cmp_lg_u32 s28, 0x800000
	s_cbranch_scc1 .Lscan_cons_chunk
	v_add_f32_dpp v130, v130, v130 row_ror:8 row_mask:0xf bank_mask:0xc
	v_add_f32_dpp v130, v122, v122 row_ror:8 row_mask:0xf bank_mask:0x3
	v_add_f32_dpp v131, v131, v131 row_ror:8 row_mask:0xf bank_mask:0xc
	v_add_f32_dpp v131, v123, v123 row_ror:8 row_mask:0xf bank_mask:0x3
	v_add_f32_dpp v132, v132, v132 row_ror:8 row_mask:0xf bank_mask:0xc
	v_add_f32_dpp v132, v124, v124 row_ror:8 row_mask:0xf bank_mask:0x3
	v_add_f32_dpp v133, v133, v133 row_ror:8 row_mask:0xf bank_mask:0xc
	v_add_f32_dpp v133, v125, v125 row_ror:8 row_mask:0xf bank_mask:0x3
	v_add_f32_dpp v134, v134, v134 row_ror:8 row_mask:0xf bank_mask:0xc
	v_add_f32_dpp v134, v126, v126 row_ror:8 row_mask:0xf bank_mask:0x3
	v_add_f32_dpp v135, v135, v135 row_ror:8 row_mask:0xf bank_mask:0xc
	v_add_f32_dpp v135, v127, v127 row_ror:8 row_mask:0xf bank_mask:0x3
	v_add_f32_dpp v136, v136, v136 row_ror:8 row_mask:0xf bank_mask:0xc
	v_add_f32_dpp v136, v128, v128 row_ror:8 row_mask:0xf bank_mask:0x3
	v_add_f32_dpp v137, v137, v137 row_ror:8 row_mask:0xf bank_mask:0xc
	v_add_f32_dpp v137, v129, v129 row_ror:8 row_mask:0xf bank_mask:0x3
	v_add_f32_dpp v134, v134, v134 row_ror:4 row_mask:0xf bank_mask:0xa
	v_add_f32_dpp v134, v130, v130 row_ror:12 row_mask:0xf bank_mask:0x5
	v_add_f32_dpp v135, v135, v135 row_ror:4 row_mask:0xf bank_mask:0xa
	v_add_f32_dpp v135, v131, v131 row_ror:12 row_mask:0xf bank_mask:0x5
	v_add_f32_dpp v136, v136, v136 row_ror:4 row_mask:0xf bank_mask:0xa
	v_add_f32_dpp v136, v132, v132 row_ror:12 row_mask:0xf bank_mask:0x5
	v_add_f32_dpp v137, v137, v137 row_ror:4 row_mask:0xf bank_mask:0xa
	v_add_f32_dpp v137, v133, v133 row_ror:12 row_mask:0xf bank_mask:0x5
	v_cndmask_b32_e64 v62, v136, v134, s[38:39]
	v_cndmask_b32_e64 v63, v134, v136, s[38:39]
	v_cndmask_b32_e64 v64, v137, v135, s[38:39]
	v_cndmask_b32_e64 v65, v135, v137, s[38:39]
	v_add_f32_dpp v62, v63, v62 quad_perm:[2,3,0,1] row_mask:0xf bank_mask:0xf bound_ctrl:1
	s_nop 0
	v_add_f32_dpp v63, v65, v64 quad_perm:[2,3,0,1] row_mask:0xf bank_mask:0xf bound_ctrl:1
	v_cndmask_b32_e64 v65, v63, v62, s[40:41]
	v_cndmask_b32_e64 v62, v62, v63, s[40:41]
	s_nop 1
	v_add_f32_dpp v62, v62, v65 quad_perm:[1,0,3,2] row_mask:0xf bank_mask:0xf bound_ctrl:1
	v_cvt_pk_bf16_f32 v62, v62, v62
	global_store_short v[2:3], v62, off
	s_branch .LBB0_53
